# two more non-BAR fragment-read runs hoisted to the start of their W block (write-address temp renamed to v250 / lagged row-sum add moved up)
# baseline (speedup 1.0000x reference)
.LBB0_641:
	s_add_i32 s24, s23, -7
	s_lshl_b32 s92, s24, 13
	s_add_u32 vcc_lo, s100, s92
	s_addc_u32 vcc_hi, s101, 0
	global_load_dwordx4 v[52:55], v248, vcc
	s_add_i32 s24, s23, -8
	s_lshl_b32 s92, s24, 7
	s_add_u32 vcc_lo, s98, s92
	s_addc_u32 vcc_hi, s99, 0
	global_load_dwordx4 v[56:59], v249, vcc
	s_mul_i32 s26, s25, 0x2400
	s_add_i32 s24, s23, -7
	s_add_i32 s27, s26, 0xffffdc00
	s_cmp_lg_u32 s25, 0
	s_cselect_b32 s27, s27, 0x9000
	v_add_u32_e32 v1, s27, v163
	ds_read_b128 v[60:63], v1 offset:36864
	ds_read_b128 v[114:117], v1 offset:36896
	ds_read_b128 v[118:121], v1 offset:41472
	ds_read_b128 v[134:137], v1 offset:41504
	ds_read_b128 v[146:149], v1 offset:36928
	ds_read_b128 v[150:153], v1 offset:36960
	ds_read_b128 v[196:199], v1 offset:41536
	ds_read_b128 v[200:203], v1 offset:41568
	s_setprio 3
	v_cvt_pk_bf16_f32 v204, v102, v103
	v_cvt_pk_bf16_f32 v205, v104, v105
	v_cvt_pk_bf16_f32 v206, v98, v99
	v_cvt_pk_bf16_f32 v207, v100, v101
	s_waitcnt lgkmcnt(7)
	s_nop 0
	v_mfma_f32_32x32x16_bf16 v[18:33], v[60:63], v[204:207], v[18:33]
	v_add_f32_e32 v1, v102, v103
	v_add_f32_e32 v1, v1, v104
	v_add_f32_e32 v1, v1, v105
	s_waitcnt lgkmcnt(5)
	v_mfma_f32_32x32x16_bf16 v[2:17], v[118:121], v[204:207], v[2:17]
	v_cvt_pk_bf16_f32 v60, v194, v187
	v_cvt_pk_bf16_f32 v61, v186, v185
	v_cvt_pk_bf16_f32 v62, v133, v132
	v_cvt_pk_bf16_f32 v63, v131, v130
	v_add_f32_e32 v1, v1, v98
	v_add_f32_e32 v1, v1, v99
	v_add_f32_e32 v1, v1, v100
	v_add_f32_e32 v1, v1, v101
	s_nop 0
	v_mfma_f32_32x32x16_bf16 v[18:33], v[114:117], v[60:63], v[18:33]
	v_add_f32_e32 v1, v1, v194
	v_add_f32_e32 v1, v1, v187
	v_add_f32_e32 v1, v1, v186
	v_add_f32_e32 v1, v1, v185
	s_waitcnt lgkmcnt(4)
	v_mfma_f32_32x32x16_bf16 v[2:17], v[134:137], v[60:63], v[2:17]
	v_cvt_pk_bf16_f32 v98, v129, v128
	v_cvt_pk_bf16_f32 v99, v127, v126
	v_cvt_pk_bf16_f32 v100, v125, v124
	v_cvt_pk_bf16_f32 v101, v123, v122
	v_add_f32_e32 v1, v1, v133
	v_add_f32_e32 v1, v1, v132
	v_add_f32_e32 v1, v1, v131
	v_add_f32_e32 v1, v1, v130
	s_waitcnt lgkmcnt(3)
	v_mfma_f32_32x32x16_bf16 v[18:33], v[146:149], v[98:101], v[18:33]
	v_add_f32_e32 v1, v1, v129
	v_add_f32_e32 v1, v1, v128
	v_add_f32_e32 v1, v1, v127
	v_add_f32_e32 v1, v1, v126
	s_waitcnt lgkmcnt(1)
	v_mfma_f32_32x32x16_bf16 v[2:17], v[196:199], v[98:101], v[2:17]
	v_cvt_pk_bf16_f32 v60, v109, v108
	v_cvt_pk_bf16_f32 v61, v107, v106
	v_cvt_pk_bf16_f32 v62, v113, v112
	v_cvt_pk_bf16_f32 v63, v111, v110
	v_add_f32_e32 v1, v1, v125
	v_add_f32_e32 v1, v1, v124
	v_add_f32_e32 v1, v1, v123
	v_add_f32_e32 v1, v1, v122
	s_nop 0
	v_mfma_f32_32x32x16_bf16 v[18:33], v[150:153], v[60:63], v[18:33]
	v_add_f32_e32 v1, v1, v109
	v_add_f32_e32 v1, v1, v108
	v_add_f32_e32 v1, v1, v107
	v_add_f32_e32 v1, v1, v106
	s_waitcnt lgkmcnt(0)
	v_mfma_f32_32x32x16_bf16 v[2:17], v[200:203], v[60:63], v[2:17]
	v_add_f32_e32 v1, v1, v113
	v_add_f32_e32 v1, v1, v112
	v_add_f32_e32 v1, v1, v111
	v_add_f32_e32 v1, v1, v110
	s_setprio 2
	s_waitcnt lgkmcnt(0)
	s_barrier
	ds_read_b128 v[240:243], v165 offset:18432
	ds_read_b128 v[244:247], v165 offset:23040
	ds_read_b128 v[130:133], v165 offset:18464
	ds_read_b128 v[146:149], v165 offset:23072
	s_waitcnt lgkmcnt(2)
	v_mfma_f32_32x32x16_bf16 v[114:129], v[240:243], v[158:161], v[34:49]
	v_exp_f32_e32 v185, v82
	v_exp_f32_e32 v186, v83
	v_exp_f32_e32 v187, v84
	v_exp_f32_e32 v194, v85
	v_exp_f32_e32 v195, v86
	v_exp_f32_e32 v196, v87
	v_exp_f32_e32 v197, v88
	v_exp_f32_e32 v198, v89
	s_waitcnt lgkmcnt(1)
	v_mfma_f32_32x32x16_bf16 v[98:113], v[244:247], v[158:161], v[34:49]
	v_exp_f32_e32 v199, v90
	v_exp_f32_e32 v200, v91
	v_exp_f32_e32 v201, v92
	v_exp_f32_e32 v202, v93
	v_exp_f32_e32 v134, v94
	v_exp_f32_e32 v135, v95
	v_exp_f32_e32 v136, v96
	v_exp_f32_e32 v137, v97
	v_mfma_f32_32x32x16_bf16 v[114:129], v[130:133], v[154:157], v[114:129]
	v_exp_f32_e32 v96, v66
	v_exp_f32_e32 v97, v67
	v_exp_f32_e32 v203, v68
	v_exp_f32_e32 v204, v69
	v_exp_f32_e32 v130, v70
	v_exp_f32_e32 v131, v71
	v_exp_f32_e32 v132, v72
	v_exp_f32_e32 v133, v73
	s_waitcnt lgkmcnt(0)
	v_mfma_f32_32x32x16_bf16 v[98:113], v[146:149], v[154:157], v[98:113]
	v_exp_f32_e32 v205, v74
	v_exp_f32_e32 v206, v75
	v_exp_f32_e32 v207, v76
	v_exp_f32_e32 v208, v77
	v_exp_f32_e32 v209, v78
	v_exp_f32_e32 v210, v79
	v_exp_f32_e32 v211, v80
	v_exp_f32_e32 v212, v81
	v_add_u32_e32 v88, s26, v163
	ds_read_b128 v[240:243], v165 offset:27648
	ds_read_b128 v[244:247], v165 offset:32256
	ds_read_b128 v[60:63], v88 offset:41472
	ds_read_b128 v[64:67], v88 offset:36864
	ds_read_b128 v[68:71], v88 offset:36896
	ds_read_b128 v[72:75], v88 offset:41504
	ds_read_b128 v[76:79], v88 offset:36928
	ds_read_b128 v[80:83], v88 offset:41536
	ds_read_b128 v[84:87], v88 offset:36960
	ds_read_b128 v[88:91], v88 offset:41568
	s_cmp_gt_i32 s25, 2
	s_cselect_b32 s27, -3, 2
	s_add_i32 s27, s27, s25
	s_add_i32 s26, s23, -6
	s_mulk_i32 s27, 0x2400
	s_min_u32 s26, s26, s13
	v_add_u32_e32 v51, s27, v182
	s_min_u32 s24, s24, s13
	s_lshl_b32 s92, s26, 13
	s_waitcnt vmcnt(3)
	ds_write_b128 v182, v[138:141]
	s_waitcnt vmcnt(2)
	ds_write_b128 v51, v[142:145] offset:36864
	v_add_f32_e32 v1, v50, v1
	s_add_u32 vcc_lo, s100, s92
	s_addc_u32 vcc_hi, s101, 0
	global_load_dwordx4 v[146:149], v248, vcc
	s_lshl_b32 s92, s24, 7
	s_add_u32 vcc_lo, s98, s92
	s_addc_u32 vcc_hi, s99, 0
	global_load_dwordx4 v[150:153], v249, vcc
	s_add_i32 s27, s25, 1
	s_setprio 1
	v_cvt_pk_bf16_f32 v92, v185, v186
	v_cvt_pk_bf16_f32 v93, v187, v194
	v_cvt_pk_bf16_f32 v94, v195, v196
	v_cvt_pk_bf16_f32 v95, v197, v198
	s_waitcnt lgkmcnt(8)
	s_nop 0
	v_mfma_f32_32x32x16_bf16 v[18:33], v[64:67], v[92:95], v[18:33]
	v_add_f32_e32 v213, v185, v186
	v_add_f32_e32 v213, v213, v187
	v_add_f32_e32 v213, v213, v194
	s_nop 0
	v_mfma_f32_32x32x16_bf16 v[2:17], v[60:63], v[92:95], v[2:17]
	v_cvt_pk_bf16_f32 v64, v199, v200
	v_cvt_pk_bf16_f32 v65, v201, v202
	v_cvt_pk_bf16_f32 v66, v134, v135
	v_cvt_pk_bf16_f32 v67, v136, v137
	v_add_f32_e32 v213, v213, v195
	v_add_f32_e32 v213, v213, v196
	v_add_f32_e32 v213, v213, v197
	v_add_f32_e32 v213, v213, v198
	s_waitcnt lgkmcnt(7)
	v_mfma_f32_32x32x16_bf16 v[18:33], v[68:71], v[64:67], v[18:33]
	v_add_f32_e32 v213, v213, v199
	v_add_f32_e32 v213, v213, v200
	v_add_f32_e32 v213, v213, v201
	v_add_f32_e32 v213, v213, v202
	s_waitcnt lgkmcnt(6)
	v_mfma_f32_32x32x16_bf16 v[2:17], v[72:75], v[64:67], v[2:17]
	v_cvt_pk_bf16_f32 v60, v96, v97
	v_cvt_pk_bf16_f32 v61, v203, v204
	v_cvt_pk_bf16_f32 v62, v130, v131
	v_cvt_pk_bf16_f32 v63, v132, v133
	v_add_f32_e32 v213, v213, v134
	v_add_f32_e32 v213, v213, v135
	v_add_f32_e32 v213, v213, v136
	v_add_f32_e32 v213, v213, v137
	s_waitcnt lgkmcnt(5)
	v_mfma_f32_32x32x16_bf16 v[18:33], v[76:79], v[60:63], v[18:33]
	v_add_f32_e32 v213, v213, v96
	v_add_f32_e32 v213, v213, v97
	v_add_f32_e32 v213, v213, v203
	v_add_f32_e32 v213, v213, v204
	s_waitcnt lgkmcnt(4)
	v_mfma_f32_32x32x16_bf16 v[2:17], v[80:83], v[60:63], v[2:17]
	v_cvt_pk_bf16_f32 v64, v205, v206
	v_cvt_pk_bf16_f32 v65, v207, v208
	v_cvt_pk_bf16_f32 v66, v209, v210
	v_cvt_pk_bf16_f32 v67, v211, v212
	v_add_f32_e32 v213, v213, v130
	v_add_f32_e32 v213, v213, v131
	v_add_f32_e32 v213, v213, v132
	v_add_f32_e32 v213, v213, v133
	s_waitcnt lgkmcnt(3)
	v_mfma_f32_32x32x16_bf16 v[18:33], v[84:87], v[64:67], v[18:33]
	v_add_f32_e32 v213, v213, v205
	v_add_f32_e32 v213, v213, v206
	v_add_f32_e32 v213, v213, v207
	v_add_f32_e32 v213, v213, v208
	s_waitcnt lgkmcnt(2)
	v_mfma_f32_32x32x16_bf16 v[2:17], v[88:91], v[64:67], v[2:17]
	v_add_f32_e32 v213, v213, v209
	v_add_f32_e32 v213, v213, v210
	v_add_f32_e32 v213, v213, v211
	v_add_f32_e32 v213, v213, v212
	s_setprio 0
	ds_read_b128 v[64:67], v165 offset:27680
	ds_read_b128 v[72:75], v165 offset:32288
	s_cmp_lg_u32 s25, 4
	s_cselect_b32 s24, s27, 0
	s_waitcnt lgkmcnt(2)
	v_mfma_f32_32x32x16_bf16 v[130:145], v[240:243], v[158:161], v[34:49]
	v_exp_f32_e32 v185, v114
	v_exp_f32_e32 v186, v115
	v_exp_f32_e32 v187, v116
	v_exp_f32_e32 v194, v117
	v_exp_f32_e32 v195, v118
	v_exp_f32_e32 v196, v119
	v_exp_f32_e32 v197, v120
	v_exp_f32_e32 v198, v121
	s_waitcnt lgkmcnt(1)
	v_mfma_f32_32x32x16_bf16 v[82:97], v[244:247], v[158:161], v[34:49]
	v_exp_f32_e32 v199, v122
	v_exp_f32_e32 v200, v123
	v_exp_f32_e32 v201, v124
	v_exp_f32_e32 v202, v125
	v_exp_f32_e32 v122, v126
	v_exp_f32_e32 v123, v127
	v_exp_f32_e32 v124, v128
	v_exp_f32_e32 v125, v129
	v_mfma_f32_32x32x16_bf16 v[130:145], v[64:67], v[154:157], v[130:145]
	v_exp_f32_e32 v126, v98
	v_exp_f32_e32 v127, v99
	v_exp_f32_e32 v128, v100
	v_exp_f32_e32 v129, v101
	v_exp_f32_e32 v203, v102
	v_exp_f32_e32 v204, v103
	v_exp_f32_e32 v205, v104
	v_exp_f32_e32 v206, v105
	s_waitcnt lgkmcnt(0)
	v_mfma_f32_32x32x16_bf16 v[82:97], v[72:75], v[154:157], v[82:97]
	v_exp_f32_e32 v102, v106
	v_exp_f32_e32 v103, v107
	v_exp_f32_e32 v104, v108
	v_exp_f32_e32 v105, v109
	v_exp_f32_e32 v106, v110
	v_exp_f32_e32 v107, v111
	v_exp_f32_e32 v108, v112
	v_exp_f32_e32 v109, v113
	s_cmp_gt_i32 s24, 2
	s_cselect_b32 s25, -3, 2
	s_add_i32 s25, s25, s24
	s_mulk_i32 s25, 0x2400
	v_add_u32_e32 v50, s25, v182
	s_add_i32 s25, s24, 1
	s_cmp_lg_u32 s24, 4
	s_cselect_b32 s24, s25, 0
	s_add_i32 s25, s23, -5
	s_min_u32 s25, s25, s13
	s_lshl_b32 s92, s25, 13
	s_waitcnt vmcnt(3)
	ds_write_b128 v182, v[52:55] offset:9216
	s_waitcnt vmcnt(2)
	ds_write_b128 v50, v[56:59] offset:36864
	s_add_u32 vcc_lo, s100, s92
	s_addc_u32 vcc_hi, s101, 0
	global_load_dwordx4 v[118:121], v248, vcc
	s_lshl_b32 s92, s26, 7
	s_add_u32 vcc_lo, s98, s92
	s_addc_u32 vcc_hi, s99, 0
	global_load_dwordx4 v[114:117], v249, vcc
	s_mul_i32 s26, s24, 0x2400
	s_add_i32 s27, s26, 0xffffdc00
	s_cmp_lg_u32 s24, 0
	s_cselect_b32 s27, s27, 0x9000
	v_add_u32_e32 v78, s27, v163
	ds_read_b128 v[50:53], v78 offset:36864
	ds_read_b128 v[54:57], v78 offset:36896
	ds_read_b128 v[58:61], v78 offset:41472
	ds_read_b128 v[62:65], v78 offset:41504
	ds_read_b128 v[66:69], v78 offset:36928
	ds_read_b128 v[70:73], v78 offset:36960
	ds_read_b128 v[74:77], v78 offset:41536
	ds_read_b128 v[78:81], v78 offset:41568
	s_setprio 3
	v_cvt_pk_bf16_f32 v98, v185, v186
	v_cvt_pk_bf16_f32 v99, v187, v194
	v_cvt_pk_bf16_f32 v100, v195, v196
	v_cvt_pk_bf16_f32 v101, v197, v198
	s_waitcnt lgkmcnt(7)
	s_nop 0
	v_mfma_f32_32x32x16_bf16 v[18:33], v[50:53], v[98:101], v[18:33]
	v_add_f32_e32 v110, v185, v186
	v_add_f32_e32 v110, v110, v187
	v_add_f32_e32 v110, v110, v194
	s_waitcnt lgkmcnt(5)
	v_mfma_f32_32x32x16_bf16 v[2:17], v[58:61], v[98:101], v[2:17]
	v_cvt_pk_bf16_f32 v50, v199, v200
	v_cvt_pk_bf16_f32 v51, v201, v202
	v_cvt_pk_bf16_f32 v52, v122, v123
	v_cvt_pk_bf16_f32 v53, v124, v125
	v_add_f32_e32 v110, v110, v195
	v_add_f32_e32 v110, v110, v196
	v_add_f32_e32 v110, v110, v197
	v_add_f32_e32 v110, v110, v198
	s_nop 0
	v_mfma_f32_32x32x16_bf16 v[18:33], v[54:57], v[50:53], v[18:33]
	v_add_f32_e32 v110, v110, v199
	v_add_f32_e32 v110, v110, v200
	v_add_f32_e32 v110, v110, v201
	v_add_f32_e32 v110, v110, v202
	s_waitcnt lgkmcnt(4)
	v_mfma_f32_32x32x16_bf16 v[2:17], v[62:65], v[50:53], v[2:17]
	v_cvt_pk_bf16_f32 v54, v126, v127
	v_cvt_pk_bf16_f32 v55, v128, v129
	v_cvt_pk_bf16_f32 v56, v203, v204
	v_cvt_pk_bf16_f32 v57, v205, v206
	v_add_f32_e32 v110, v110, v122
	v_add_f32_e32 v110, v110, v123
	v_add_f32_e32 v110, v110, v124
	v_add_f32_e32 v110, v110, v125
	s_waitcnt lgkmcnt(3)
	v_mfma_f32_32x32x16_bf16 v[18:33], v[66:69], v[54:57], v[18:33]
	v_add_f32_e32 v110, v110, v126
	v_add_f32_e32 v110, v110, v127
	v_add_f32_e32 v110, v110, v128
	v_add_f32_e32 v110, v110, v129
	s_waitcnt lgkmcnt(1)
	v_mfma_f32_32x32x16_bf16 v[2:17], v[74:77], v[54:57], v[2:17]
	v_cvt_pk_bf16_f32 v50, v102, v103
	v_cvt_pk_bf16_f32 v51, v104, v105
	v_cvt_pk_bf16_f32 v52, v106, v107
	v_cvt_pk_bf16_f32 v53, v108, v109
	v_add_f32_e32 v110, v110, v203
	v_add_f32_e32 v110, v110, v204
	v_add_f32_e32 v110, v110, v205
	v_add_f32_e32 v110, v110, v206
	s_nop 0
	v_mfma_f32_32x32x16_bf16 v[18:33], v[70:73], v[50:53], v[18:33]
	v_add_f32_e32 v110, v110, v102
	v_add_f32_e32 v110, v110, v103
	v_add_f32_e32 v110, v110, v104
	v_add_f32_e32 v110, v110, v105
	s_waitcnt lgkmcnt(0)
	v_mfma_f32_32x32x16_bf16 v[2:17], v[78:81], v[50:53], v[2:17]
	v_add_f32_e32 v110, v110, v106
	v_add_f32_e32 v110, v110, v107
	v_add_f32_e32 v110, v110, v108
	v_add_f32_e32 v110, v110, v109
	s_setprio 2
	s_waitcnt lgkmcnt(0)
	s_barrier
	ds_read_b128 v[240:243], v165
	ds_read_b128 v[244:247], v165 offset:4608
	ds_read_b128 v[102:105], v165 offset:32
	ds_read_b128 v[106:109], v165 offset:4640
	v_add_f32_e32 v1, v1, v213
	s_waitcnt lgkmcnt(2)
	v_mfma_f32_32x32x16_bf16 v[66:81], v[240:243], v[158:161], v[34:49]
	v_exp_f32_e32 v185, v130
	v_exp_f32_e32 v186, v131
	v_exp_f32_e32 v187, v132
	v_exp_f32_e32 v194, v133
	v_exp_f32_e32 v195, v134
	v_exp_f32_e32 v196, v135
	v_exp_f32_e32 v197, v136
	v_exp_f32_e32 v198, v137
	v_mfma_f32_32x32x16_bf16 v[50:65], v[244:247], v[158:161], v[34:49]
	v_exp_f32_e32 v134, v138
	v_exp_f32_e32 v135, v139
	v_exp_f32_e32 v136, v140
	v_exp_f32_e32 v137, v141
	v_exp_f32_e32 v138, v142
	v_exp_f32_e32 v139, v143
	v_exp_f32_e32 v140, v144
	v_exp_f32_e32 v141, v145
	s_waitcnt lgkmcnt(1)
	v_mfma_f32_32x32x16_bf16 v[66:81], v[102:105], v[154:157], v[66:81]
	v_exp_f32_e32 v142, v82
	v_exp_f32_e32 v143, v83
	v_exp_f32_e32 v144, v84
	v_exp_f32_e32 v145, v85
	v_exp_f32_e32 v199, v86
	v_exp_f32_e32 v200, v87
	v_exp_f32_e32 v201, v88
	v_exp_f32_e32 v202, v89
	s_waitcnt lgkmcnt(0)
	v_mfma_f32_32x32x16_bf16 v[50:65], v[106:109], v[154:157], v[50:65]
	v_exp_f32_e32 v203, v90
	v_exp_f32_e32 v204, v91
	v_exp_f32_e32 v205, v92
	v_exp_f32_e32 v206, v93
	v_exp_f32_e32 v207, v94
	v_exp_f32_e32 v208, v95
	v_exp_f32_e32 v209, v96
	v_exp_f32_e32 v210, v97
	v_add_f32_e32 v1, v1, v110
	v_add_u32_e32 v111, s26, v163
	ds_read_b128 v[240:243], v165 offset:9216
	ds_read_b128 v[244:247], v165 offset:13824
	ds_read_b128 v[82:85], v111 offset:41472
	ds_read_b128 v[86:89], v111 offset:36864
	ds_read_b128 v[90:93], v111 offset:36896
	ds_read_b128 v[94:97], v111 offset:41504
	ds_read_b128 v[98:101], v111 offset:36928
	ds_read_b128 v[102:105], v111 offset:41536
	ds_read_b128 v[106:109], v111 offset:36960
	ds_read_b128 v[110:113], v111 offset:41568
	s_cmp_gt_i32 s24, 2
	s_cselect_b32 s27, -3, 2
	s_add_i32 s27, s27, s24
	s_mulk_i32 s27, 0x2400
	v_add_u32_e32 v250, s27, v182
	s_mov_b32 s27, 0x18950000
	s_waitcnt vmcnt(3)
	ds_write_b128 v182, v[146:149] offset:18432
	s_waitcnt vmcnt(2)
	ds_write_b128 v250, v[150:153] offset:36864
	s_add_i32 s92, s23, -4
	s_lshl_b32 s92, s92, 13
	s_add_u32 vcc_lo, s100, s92
	s_addc_u32 vcc_hi, s101, 0
	global_load_dwordx4 v[126:129], v248, vcc
	s_lshl_b32 s92, s25, 7
	s_add_u32 vcc_lo, s98, s92
	s_addc_u32 vcc_hi, s99, 0
	global_load_dwordx4 v[122:125], v249, vcc
	s_add_i32 s26, s24, 1
	s_setprio 1
	v_cvt_pk_bf16_f32 v130, v185, v186
	v_cvt_pk_bf16_f32 v131, v187, v194
	v_cvt_pk_bf16_f32 v132, v195, v196
	v_cvt_pk_bf16_f32 v133, v197, v198
	s_waitcnt lgkmcnt(8)
	s_nop 0
	v_mfma_f32_32x32x16_bf16 v[18:33], v[86:89], v[130:133], v[18:33]
	v_add_f32_e32 v146, v185, v186
	v_add_f32_e32 v146, v146, v187
	v_add_f32_e32 v146, v146, v194
	s_nop 0
	v_mfma_f32_32x32x16_bf16 v[2:17], v[82:85], v[130:133], v[2:17]
	v_cvt_pk_bf16_f32 v86, v134, v135
	v_cvt_pk_bf16_f32 v87, v136, v137
	v_cvt_pk_bf16_f32 v88, v138, v139
	v_cvt_pk_bf16_f32 v89, v140, v141
	v_add_f32_e32 v146, v146, v195
	v_add_f32_e32 v146, v146, v196
	v_add_f32_e32 v146, v146, v197
	v_add_f32_e32 v146, v146, v198
	s_waitcnt lgkmcnt(7)
	v_mfma_f32_32x32x16_bf16 v[18:33], v[90:93], v[86:89], v[18:33]
	v_add_f32_e32 v146, v146, v134
	v_add_f32_e32 v146, v146, v135
	v_add_f32_e32 v146, v146, v136
	v_add_f32_e32 v146, v146, v137
	s_waitcnt lgkmcnt(6)
	v_mfma_f32_32x32x16_bf16 v[2:17], v[94:97], v[86:89], v[2:17]
	v_cvt_pk_bf16_f32 v82, v142, v143
	v_cvt_pk_bf16_f32 v83, v144, v145
	v_cvt_pk_bf16_f32 v84, v199, v200
	v_cvt_pk_bf16_f32 v85, v201, v202
	v_add_f32_e32 v146, v146, v138
	v_add_f32_e32 v146, v146, v139
	v_add_f32_e32 v146, v146, v140
	v_add_f32_e32 v146, v146, v141
	s_waitcnt lgkmcnt(5)
	v_mfma_f32_32x32x16_bf16 v[18:33], v[98:101], v[82:85], v[18:33]
	v_add_f32_e32 v146, v146, v142
	v_add_f32_e32 v146, v146, v143
	v_add_f32_e32 v146, v146, v144
	v_add_f32_e32 v146, v146, v145
	s_waitcnt lgkmcnt(4)
	v_mfma_f32_32x32x16_bf16 v[2:17], v[102:105], v[82:85], v[2:17]
	v_cvt_pk_bf16_f32 v86, v203, v204
	v_cvt_pk_bf16_f32 v87, v205, v206
	v_cvt_pk_bf16_f32 v88, v207, v208
	v_cvt_pk_bf16_f32 v89, v209, v210
	v_add_f32_e32 v146, v146, v199
	v_add_f32_e32 v146, v146, v200
	v_add_f32_e32 v146, v146, v201
	v_add_f32_e32 v146, v146, v202
	s_waitcnt lgkmcnt(3)
	v_mfma_f32_32x32x16_bf16 v[18:33], v[106:109], v[86:89], v[18:33]
	v_add_f32_e32 v146, v146, v203
	v_add_f32_e32 v146, v146, v204
	v_add_f32_e32 v146, v146, v205
	v_add_f32_e32 v146, v146, v206
	s_waitcnt lgkmcnt(2)
	v_mfma_f32_32x32x16_bf16 v[2:17], v[110:113], v[86:89], v[2:17]
	v_add_f32_e32 v146, v146, v207
	v_add_f32_e32 v146, v146, v208
	v_add_f32_e32 v146, v146, v209
	v_add_f32_e32 v146, v146, v210
	s_setprio 0
	ds_read_b128 v[130:133], v165 offset:9248
	ds_read_b128 v[138:141], v165 offset:13856
	s_cmp_lg_u32 s24, 4
	s_cselect_b32 s24, s26, 0
	s_waitcnt lgkmcnt(2)
	v_mfma_f32_32x32x16_bf16 v[98:113], v[240:243], v[158:161], v[34:49]
	v_exp_f32_e32 v142, v66
	v_exp_f32_e32 v143, v67
	v_exp_f32_e32 v144, v68
	v_exp_f32_e32 v145, v69
	v_exp_f32_e32 v147, v70
	v_exp_f32_e32 v148, v71
	v_exp_f32_e32 v149, v72
	v_exp_f32_e32 v150, v73
	s_waitcnt lgkmcnt(1)
	v_mfma_f32_32x32x16_bf16 v[82:97], v[244:247], v[158:161], v[34:49]
	v_exp_f32_e32 v151, v74
	v_exp_f32_e32 v152, v75
	v_exp_f32_e32 v153, v76
	v_exp_f32_e32 v178, v77
	v_exp_f32_e32 v134, v78
	v_exp_f32_e32 v135, v79
	v_exp_f32_e32 v136, v80
	v_exp_f32_e32 v137, v81
	v_mfma_f32_32x32x16_bf16 v[98:113], v[130:133], v[154:157], v[98:113]
	v_exp_f32_e32 v179, v50
	v_exp_f32_e32 v185, v51
	v_exp_f32_e32 v186, v52
	v_exp_f32_e32 v187, v53
	v_exp_f32_e32 v194, v54
	v_exp_f32_e32 v195, v55
	v_exp_f32_e32 v196, v56
	v_exp_f32_e32 v197, v57
	s_waitcnt lgkmcnt(0)
	v_mfma_f32_32x32x16_bf16 v[82:97], v[138:141], v[154:157], v[82:97]
	v_exp_f32_e32 v198, v58
	v_exp_f32_e32 v199, v59
	v_exp_f32_e32 v200, v60
	v_exp_f32_e32 v201, v61
	v_exp_f32_e32 v138, v62
	v_exp_f32_e32 v139, v63
	v_exp_f32_e32 v140, v64
	v_exp_f32_e32 v141, v65
	s_cmp_gt_i32 s24, 2
	s_cselect_b32 s25, -3, 2
	s_add_i32 s25, s25, s24
	s_mulk_i32 s25, 0x2400
	v_add_u32_e32 v50, s25, v182
	s_add_i32 s25, s24, 1
	s_cmp_lg_u32 s24, 4
	s_cselect_b32 s25, s25, 0
	s_add_i32 s24, s23, -3
	s_min_u32 s26, s24, s13
	s_lshl_b32 s92, s26, 13
	s_waitcnt vmcnt(3)
	ds_write_b128 v182, v[118:121] offset:27648
	s_waitcnt vmcnt(2)
	ds_write_b128 v50, v[114:117] offset:36864
	s_add_u32 vcc_lo, s100, s92
	s_addc_u32 vcc_hi, s101, 0
	global_load_dwordx4 v[118:121], v248, vcc
	s_add_i32 s92, s23, -4
	s_lshl_b32 s92, s92, 7
	s_add_u32 vcc_lo, s98, s92
	s_addc_u32 vcc_hi, s99, 0
	global_load_dwordx4 v[114:117], v249, vcc
	s_mul_i32 s27, s25, 0x2400
	s_add_i32 s28, s27, 0xffffdc00
	s_cmp_lg_u32 s25, 0
	s_cselect_b32 s28, s28, 0x9000
	v_add_u32_e32 v78, s28, v163
	ds_read_b128 v[50:53], v78 offset:36864
	ds_read_b128 v[54:57], v78 offset:36896
	ds_read_b128 v[58:61], v78 offset:41472
	ds_read_b128 v[62:65], v78 offset:41504
	ds_read_b128 v[66:69], v78 offset:36928
	ds_read_b128 v[70:73], v78 offset:36960
	ds_read_b128 v[74:77], v78 offset:41536
	ds_read_b128 v[78:81], v78 offset:41568
	s_setprio 3
	v_cvt_pk_bf16_f32 v130, v142, v143
	v_cvt_pk_bf16_f32 v131, v144, v145
	v_cvt_pk_bf16_f32 v132, v147, v148
	v_cvt_pk_bf16_f32 v133, v149, v150
	s_waitcnt lgkmcnt(7)
	s_nop 0
	v_mfma_f32_32x32x16_bf16 v[18:33], v[50:53], v[130:133], v[18:33]
	v_add_f32_e32 v176, v142, v143
	v_add_f32_e32 v176, v176, v144
	v_add_f32_e32 v176, v176, v145
	s_waitcnt lgkmcnt(5)
	v_mfma_f32_32x32x16_bf16 v[2:17], v[58:61], v[130:133], v[2:17]
	v_cvt_pk_bf16_f32 v50, v151, v152
	v_cvt_pk_bf16_f32 v51, v153, v178
	v_cvt_pk_bf16_f32 v52, v134, v135
	v_cvt_pk_bf16_f32 v53, v136, v137
	v_add_f32_e32 v176, v176, v147
	v_add_f32_e32 v176, v176, v148
	v_add_f32_e32 v176, v176, v149
	v_add_f32_e32 v176, v176, v150
	s_nop 0
	v_mfma_f32_32x32x16_bf16 v[18:33], v[54:57], v[50:53], v[18:33]
	v_add_f32_e32 v176, v176, v151
	v_add_f32_e32 v176, v176, v152
	v_add_f32_e32 v176, v176, v153
	v_add_f32_e32 v176, v176, v178
	s_waitcnt lgkmcnt(4)
	v_mfma_f32_32x32x16_bf16 v[2:17], v[62:65], v[50:53], v[2:17]
	v_cvt_pk_bf16_f32 v54, v179, v185
	v_cvt_pk_bf16_f32 v55, v186, v187
	v_cvt_pk_bf16_f32 v56, v194, v195
	v_cvt_pk_bf16_f32 v57, v196, v197
	v_add_f32_e32 v176, v176, v134
	v_add_f32_e32 v176, v176, v135
	v_add_f32_e32 v176, v176, v136
	v_add_f32_e32 v176, v176, v137
	s_waitcnt lgkmcnt(3)
	v_mfma_f32_32x32x16_bf16 v[18:33], v[66:69], v[54:57], v[18:33]
	v_add_f32_e32 v176, v176, v179
	v_add_f32_e32 v176, v176, v185
	v_add_f32_e32 v176, v176, v186
	v_add_f32_e32 v176, v176, v187
	s_waitcnt lgkmcnt(1)
	v_mfma_f32_32x32x16_bf16 v[2:17], v[74:77], v[54:57], v[2:17]
	v_cvt_pk_bf16_f32 v50, v198, v199
	v_cvt_pk_bf16_f32 v51, v200, v201
	v_cvt_pk_bf16_f32 v52, v138, v139
	v_cvt_pk_bf16_f32 v53, v140, v141
	v_add_f32_e32 v176, v176, v194
	v_add_f32_e32 v176, v176, v195
	v_add_f32_e32 v176, v176, v196
	v_add_f32_e32 v176, v176, v197
	s_nop 0
	v_mfma_f32_32x32x16_bf16 v[18:33], v[70:73], v[50:53], v[18:33]
	v_add_f32_e32 v176, v176, v198
	v_add_f32_e32 v176, v176, v199
	v_add_f32_e32 v176, v176, v200
	v_add_f32_e32 v176, v176, v201
	s_waitcnt lgkmcnt(0)
	v_mfma_f32_32x32x16_bf16 v[2:17], v[78:81], v[50:53], v[2:17]
	v_add_f32_e32 v176, v176, v138
	v_add_f32_e32 v176, v176, v139
	v_add_f32_e32 v176, v176, v140
	v_add_f32_e32 v176, v176, v141
	s_setprio 2
	s_waitcnt lgkmcnt(0)
	s_barrier
	ds_read_b128 v[240:243], v165 offset:18432
	ds_read_b128 v[244:247], v165 offset:23040
	ds_read_b128 v[134:137], v165 offset:18464
	ds_read_b128 v[138:141], v165 offset:23072
	v_add_f32_e32 v1, v1, v146
	s_waitcnt lgkmcnt(2)
	v_mfma_f32_32x32x16_bf16 v[66:81], v[240:243], v[158:161], v[34:49]
	v_exp_f32_e32 v142, v98
	v_exp_f32_e32 v143, v99
	v_exp_f32_e32 v144, v100
	v_exp_f32_e32 v145, v101
	v_exp_f32_e32 v146, v102
	v_exp_f32_e32 v147, v103
	v_exp_f32_e32 v148, v104
	v_exp_f32_e32 v149, v105
	v_mfma_f32_32x32x16_bf16 v[50:65], v[244:247], v[158:161], v[34:49]
	v_exp_f32_e32 v150, v106
	v_exp_f32_e32 v151, v107
	v_exp_f32_e32 v152, v108
	v_exp_f32_e32 v153, v109
	v_exp_f32_e32 v177, v110
	v_exp_f32_e32 v178, v111
	v_exp_f32_e32 v179, v112
	v_exp_f32_e32 v185, v113
	s_waitcnt lgkmcnt(1)
	v_mfma_f32_32x32x16_bf16 v[66:81], v[134:137], v[154:157], v[66:81]
	v_exp_f32_e32 v186, v82
	v_exp_f32_e32 v187, v83
	v_exp_f32_e32 v194, v84
	v_exp_f32_e32 v195, v85
	v_exp_f32_e32 v134, v86
	v_exp_f32_e32 v135, v87
	v_exp_f32_e32 v136, v88
	v_exp_f32_e32 v137, v89
	s_waitcnt lgkmcnt(0)
	v_mfma_f32_32x32x16_bf16 v[50:65], v[138:141], v[154:157], v[50:65]
	v_exp_f32_e32 v196, v90
	v_exp_f32_e32 v197, v91
	v_exp_f32_e32 v198, v92
	v_exp_f32_e32 v199, v93
	v_exp_f32_e32 v138, v94
	v_exp_f32_e32 v139, v95
	v_exp_f32_e32 v140, v96
	v_exp_f32_e32 v141, v97
	s_cmp_gt_i32 s25, 2
	s_cselect_b32 s28, -3, 2
	s_waitcnt vmcnt(3)
	ds_write_b128 v182, v[126:129]
	s_add_i32 s28, s28, s25
	v_add_u32_e32 v126, s27, v163
	s_add_i32 s27, s23, -2
	s_mulk_i32 s28, 0x2400
	s_min_u32 s27, s27, s13
	v_add_u32_e32 v82, s28, v182
	s_lshl_b32 s92, s27, 13
	s_waitcnt vmcnt(2)
	ds_write_b128 v82, v[122:125] offset:36864
	ds_read_b128 v[240:243], v165 offset:27648
	ds_read_b128 v[244:247], v165 offset:32256
	ds_read_b128 v[82:85], v126 offset:41472
	ds_read_b128 v[86:89], v126 offset:36864
	ds_read_b128 v[90:93], v126 offset:36896
	ds_read_b128 v[94:97], v126 offset:41504
	ds_read_b128 v[106:109], v126 offset:36928
	ds_read_b128 v[110:113], v126 offset:41536
	ds_read_b128 v[122:125], v126 offset:36960
	ds_read_b128 v[126:129], v126 offset:41568
	s_add_u32 vcc_lo, s100, s92
	s_addc_u32 vcc_hi, s101, 0
	global_load_dwordx4 v[98:101], v248, vcc
	s_lshl_b32 s92, s26, 7
	s_add_u32 vcc_lo, s98, s92
	s_addc_u32 vcc_hi, s99, 0
	global_load_dwordx4 v[102:105], v249, vcc
	v_add_f32_e32 v1, v1, v176
	s_add_i32 s28, s25, 1
	s_setprio 1
	v_cvt_pk_bf16_f32 v130, v142, v143
	v_cvt_pk_bf16_f32 v131, v144, v145
	v_cvt_pk_bf16_f32 v132, v146, v147
	v_cvt_pk_bf16_f32 v133, v148, v149
	s_waitcnt lgkmcnt(6)
	s_nop 0
	v_mfma_f32_32x32x16_bf16 v[18:33], v[86:89], v[130:133], v[18:33]
	v_add_f32_e32 v176, v142, v143
	v_add_f32_e32 v176, v176, v144
	v_add_f32_e32 v176, v176, v145
	s_nop 0
	v_mfma_f32_32x32x16_bf16 v[2:17], v[82:85], v[130:133], v[2:17]
	v_cvt_pk_bf16_f32 v86, v150, v151
	v_cvt_pk_bf16_f32 v87, v152, v153
	v_cvt_pk_bf16_f32 v88, v177, v178
	v_cvt_pk_bf16_f32 v89, v179, v185
	v_add_f32_e32 v176, v176, v146
	v_add_f32_e32 v176, v176, v147
	v_add_f32_e32 v176, v176, v148
	v_add_f32_e32 v176, v176, v149
	s_waitcnt lgkmcnt(5)
	v_mfma_f32_32x32x16_bf16 v[18:33], v[90:93], v[86:89], v[18:33]
	v_add_f32_e32 v176, v176, v150
	v_add_f32_e32 v176, v176, v151
	v_add_f32_e32 v176, v176, v152
	v_add_f32_e32 v176, v176, v153
	s_waitcnt lgkmcnt(4)
	v_mfma_f32_32x32x16_bf16 v[2:17], v[94:97], v[86:89], v[2:17]
	v_cvt_pk_bf16_f32 v82, v186, v187
	v_cvt_pk_bf16_f32 v83, v194, v195
	v_cvt_pk_bf16_f32 v84, v134, v135
	v_cvt_pk_bf16_f32 v85, v136, v137
	v_add_f32_e32 v176, v176, v177
	v_add_f32_e32 v176, v176, v178
	v_add_f32_e32 v176, v176, v179
	v_add_f32_e32 v176, v176, v185
	s_waitcnt lgkmcnt(3)
	v_mfma_f32_32x32x16_bf16 v[18:33], v[106:109], v[82:85], v[18:33]
	v_add_f32_e32 v176, v176, v186
	v_add_f32_e32 v176, v176, v187
	v_add_f32_e32 v176, v176, v194
	v_add_f32_e32 v176, v176, v195
	s_waitcnt lgkmcnt(2)
	v_mfma_f32_32x32x16_bf16 v[2:17], v[110:113], v[82:85], v[2:17]
	v_cvt_pk_bf16_f32 v86, v196, v197
	v_cvt_pk_bf16_f32 v87, v198, v199
	v_cvt_pk_bf16_f32 v88, v138, v139
	v_cvt_pk_bf16_f32 v89, v140, v141
	v_add_f32_e32 v176, v176, v134
	v_add_f32_e32 v176, v176, v135
	v_add_f32_e32 v176, v176, v136
	v_add_f32_e32 v176, v176, v137
	s_waitcnt lgkmcnt(1)
	v_mfma_f32_32x32x16_bf16 v[18:33], v[122:125], v[86:89], v[18:33]
	v_add_f32_e32 v176, v176, v196
	v_add_f32_e32 v176, v176, v197
	v_add_f32_e32 v176, v176, v198
	v_add_f32_e32 v176, v176, v199
	s_waitcnt lgkmcnt(0)
	v_mfma_f32_32x32x16_bf16 v[2:17], v[126:129], v[86:89], v[2:17]
	v_add_f32_e32 v176, v176, v138
	v_add_f32_e32 v176, v176, v139
	v_add_f32_e32 v176, v176, v140
	v_add_f32_e32 v176, v176, v141
	s_setprio 0
	ds_read_b128 v[106:109], v165 offset:27680
	ds_read_b128 v[122:125], v165 offset:32288
	s_cmp_lg_u32 s25, 4
	s_cselect_b32 s25, s28, 0
	s_waitcnt lgkmcnt(2)
	v_mfma_f32_32x32x16_bf16 v[138:153], v[240:243], v[158:161], v[34:49]
	v_exp_f32_e32 v126, v66
	v_exp_f32_e32 v127, v67
	v_exp_f32_e32 v128, v68
	v_exp_f32_e32 v129, v69
	v_exp_f32_e32 v130, v70
	v_exp_f32_e32 v131, v71
	v_exp_f32_e32 v132, v72
	v_exp_f32_e32 v133, v73
	s_waitcnt lgkmcnt(1)
	v_mfma_f32_32x32x16_bf16 v[82:97], v[244:247], v[158:161], v[34:49]
	v_exp_f32_e32 v134, v74
	v_exp_f32_e32 v135, v75
	v_exp_f32_e32 v136, v76
	v_exp_f32_e32 v137, v77
	v_exp_f32_e32 v177, v78
	v_exp_f32_e32 v178, v79
	v_exp_f32_e32 v179, v80
	v_exp_f32_e32 v185, v81
	v_mfma_f32_32x32x16_bf16 v[138:153], v[106:109], v[154:157], v[138:153]
	v_exp_f32_e32 v80, v50
	v_exp_f32_e32 v81, v51
	v_exp_f32_e32 v186, v52
	v_exp_f32_e32 v187, v53
	v_exp_f32_e32 v194, v54
	v_exp_f32_e32 v195, v55
	v_exp_f32_e32 v196, v56
	v_exp_f32_e32 v197, v57
	s_waitcnt lgkmcnt(0)
	v_mfma_f32_32x32x16_bf16 v[82:97], v[122:125], v[154:157], v[82:97]
	v_exp_f32_e32 v198, v58
	v_exp_f32_e32 v199, v59
	v_exp_f32_e32 v200, v60
	v_exp_f32_e32 v201, v61
	v_exp_f32_e32 v122, v62
	v_exp_f32_e32 v123, v63
	v_exp_f32_e32 v124, v64
	v_exp_f32_e32 v125, v65
	s_cmp_gt_i32 s25, 2
	s_cselect_b32 s26, -3, 2
	s_add_i32 s26, s26, s25
	s_mulk_i32 s26, 0x2400
	v_add_u32_e32 v50, s26, v182
	s_add_i32 s26, s25, 1
	s_cmp_lg_u32 s25, 4
	s_cselect_b32 s25, s26, 0
	s_add_i32 s26, s23, -1
	s_min_u32 s26, s26, s13
	s_lshl_b32 s92, s26, 13
	s_waitcnt vmcnt(3)
	ds_write_b128 v182, v[118:121] offset:9216
	s_waitcnt vmcnt(2)
	ds_write_b128 v50, v[114:117] offset:36864
	s_add_u32 vcc_lo, s100, s92
	s_addc_u32 vcc_hi, s101, 0
	global_load_dwordx4 v[56:59], v248, vcc
	s_lshl_b32 s92, s27, 7
	s_add_u32 vcc_lo, s98, s92
	s_addc_u32 vcc_hi, s99, 0
	global_load_dwordx4 v[52:55], v249, vcc
	s_nop 0
	s_mul_i32 s27, s25, 0x2400
	s_add_i32 s28, s27, 0xffffdc00
	s_cmp_lg_u32 s25, 0
	s_cselect_b32 s28, s28, 0x9000
	v_add_u32_e32 v50, s28, v163
	ds_read_b128 v[60:63], v50 offset:36864
	ds_read_b128 v[64:67], v50 offset:36896
	ds_read_b128 v[68:71], v50 offset:41472
	ds_read_b128 v[72:75], v50 offset:41504
	ds_read_b128 v[76:79], v50 offset:36928
	ds_read_b128 v[106:109], v50 offset:36960
	ds_read_b128 v[110:113], v50 offset:41536
	ds_read_b128 v[114:117], v50 offset:41568
	s_setprio 3
	v_cvt_pk_bf16_f32 v118, v126, v127
	v_cvt_pk_bf16_f32 v119, v128, v129
	v_cvt_pk_bf16_f32 v120, v130, v131
	v_cvt_pk_bf16_f32 v121, v132, v133
	s_waitcnt lgkmcnt(7)
	s_nop 0
	v_mfma_f32_32x32x16_bf16 v[18:33], v[60:63], v[118:121], v[18:33]
	v_add_f32_e32 v50, v126, v127
	v_add_f32_e32 v50, v50, v128
	v_add_f32_e32 v50, v50, v129
	s_waitcnt lgkmcnt(5)
	v_mfma_f32_32x32x16_bf16 v[2:17], v[68:71], v[118:121], v[2:17]
	v_cvt_pk_bf16_f32 v60, v134, v135
	v_cvt_pk_bf16_f32 v61, v136, v137
	v_cvt_pk_bf16_f32 v62, v177, v178
	v_cvt_pk_bf16_f32 v63, v179, v185
	v_add_f32_e32 v50, v50, v130
	v_add_f32_e32 v50, v50, v131
	v_add_f32_e32 v50, v50, v132
	v_add_f32_e32 v50, v50, v133
	s_nop 0
	v_mfma_f32_32x32x16_bf16 v[18:33], v[64:67], v[60:63], v[18:33]
	v_add_f32_e32 v50, v50, v134
	v_add_f32_e32 v50, v50, v135
	v_add_f32_e32 v50, v50, v136
	v_add_f32_e32 v50, v50, v137
	s_waitcnt lgkmcnt(4)
	v_mfma_f32_32x32x16_bf16 v[2:17], v[72:75], v[60:63], v[2:17]
	v_cvt_pk_bf16_f32 v64, v80, v81
	v_cvt_pk_bf16_f32 v65, v186, v187
	v_cvt_pk_bf16_f32 v66, v194, v195
	v_cvt_pk_bf16_f32 v67, v196, v197
	v_add_f32_e32 v50, v50, v177
	v_add_f32_e32 v50, v50, v178
	v_add_f32_e32 v50, v50, v179
	v_add_f32_e32 v50, v50, v185
	s_waitcnt lgkmcnt(3)
	v_mfma_f32_32x32x16_bf16 v[18:33], v[76:79], v[64:67], v[18:33]
	v_add_f32_e32 v50, v50, v80
	v_add_f32_e32 v50, v50, v81
	v_add_f32_e32 v50, v50, v186
	v_add_f32_e32 v50, v50, v187
	s_waitcnt lgkmcnt(1)
	v_mfma_f32_32x32x16_bf16 v[2:17], v[110:113], v[64:67], v[2:17]
	v_cvt_pk_bf16_f32 v60, v198, v199
	v_cvt_pk_bf16_f32 v61, v200, v201
	v_cvt_pk_bf16_f32 v62, v122, v123
	v_cvt_pk_bf16_f32 v63, v124, v125
	v_add_f32_e32 v50, v50, v194
	v_add_f32_e32 v50, v50, v195
	v_add_f32_e32 v50, v50, v196
	v_add_f32_e32 v50, v50, v197
	s_nop 0
	v_mfma_f32_32x32x16_bf16 v[18:33], v[106:109], v[60:63], v[18:33]
	v_add_f32_e32 v50, v50, v198
	v_add_f32_e32 v50, v50, v199
	v_add_f32_e32 v50, v50, v200
	v_add_f32_e32 v50, v50, v201
	s_waitcnt lgkmcnt(0)
	v_mfma_f32_32x32x16_bf16 v[2:17], v[114:117], v[60:63], v[2:17]
	v_add_f32_e32 v50, v50, v122
	v_add_f32_e32 v50, v50, v123
	v_add_f32_e32 v50, v50, v124
	v_add_f32_e32 v50, v50, v125
	s_setprio 2
	s_waitcnt lgkmcnt(0)
	s_barrier
	ds_read_b128 v[240:243], v165
	ds_read_b128 v[244:247], v165 offset:4608
	ds_read_b128 v[68:71], v165 offset:32
	ds_read_b128 v[72:75], v165 offset:4640
	v_add_f32_e32 v1, v1, v176
	s_waitcnt lgkmcnt(2)
	v_mfma_f32_32x32x16_bf16 v[122:137], v[240:243], v[158:161], v[34:49]
	v_exp_f32_e32 v176, v138
	v_exp_f32_e32 v177, v139
	v_exp_f32_e32 v178, v140
	v_exp_f32_e32 v179, v141
	v_exp_f32_e32 v185, v142
	v_exp_f32_e32 v186, v143
	v_exp_f32_e32 v187, v144
	v_exp_f32_e32 v194, v145
	v_mfma_f32_32x32x16_bf16 v[106:121], v[244:247], v[158:161], v[34:49]
	v_exp_f32_e32 v195, v146
	v_exp_f32_e32 v196, v147
	v_exp_f32_e32 v197, v148
	v_exp_f32_e32 v198, v149
	v_exp_f32_e32 v146, v150
	v_exp_f32_e32 v147, v151
	v_exp_f32_e32 v148, v152
	v_exp_f32_e32 v149, v153
	s_waitcnt lgkmcnt(1)
	v_mfma_f32_32x32x16_bf16 v[122:137], v[68:71], v[154:157], v[122:137]
	v_exp_f32_e32 v150, v82
	v_exp_f32_e32 v151, v83
	v_exp_f32_e32 v152, v84
	v_exp_f32_e32 v153, v85
	v_exp_f32_e32 v199, v86
	v_exp_f32_e32 v200, v87
	v_exp_f32_e32 v201, v88
	v_exp_f32_e32 v202, v89
	s_waitcnt lgkmcnt(0)
	v_mfma_f32_32x32x16_bf16 v[106:121], v[72:75], v[154:157], v[106:121]
	v_exp_f32_e32 v203, v90
	v_exp_f32_e32 v204, v91
	v_exp_f32_e32 v205, v92
	v_exp_f32_e32 v206, v93
	v_exp_f32_e32 v207, v94
	v_exp_f32_e32 v208, v95
	v_exp_f32_e32 v209, v96
	v_exp_f32_e32 v210, v97
	v_add_u32_e32 v88, s27, v163
	ds_read_b128 v[240:243], v165 offset:9216
	ds_read_b128 v[244:247], v165 offset:13824
	ds_read_b128 v[60:63], v88 offset:41472
	ds_read_b128 v[64:67], v88 offset:36864
	ds_read_b128 v[68:71], v88 offset:36896
	ds_read_b128 v[72:75], v88 offset:41504
	ds_read_b128 v[76:79], v88 offset:36928
	ds_read_b128 v[80:83], v88 offset:41536
	ds_read_b128 v[84:87], v88 offset:36960
	ds_read_b128 v[88:91], v88 offset:41568
	s_cmp_gt_i32 s25, 2
	s_cselect_b32 s28, -3, 2
	s_add_i32 s28, s28, s25
	s_mulk_i32 s28, 0x2400
	s_min_u32 s27, s23, s13
	v_add_u32_e32 v51, s28, v182
	s_lshl_b32 s92, s27, 13
	s_waitcnt vmcnt(3)
	ds_write_b128 v182, v[98:101] offset:18432
	s_waitcnt vmcnt(2)
	ds_write_b128 v51, v[102:105] offset:36864
	v_add_f32_e32 v1, v1, v50
	s_add_u32 vcc_lo, s100, s92
	s_addc_u32 vcc_hi, s101, 0
	global_load_dwordx4 v[138:141], v248, vcc
	s_lshl_b32 s92, s26, 7
	s_add_u32 vcc_lo, s98, s92
	s_addc_u32 vcc_hi, s99, 0
	global_load_dwordx4 v[142:145], v249, vcc
	s_setprio 1
	v_mov_b32_e32 v51, v122
	v_cvt_pk_bf16_f32 v92, v176, v177
	v_cvt_pk_bf16_f32 v93, v178, v179
	v_cvt_pk_bf16_f32 v94, v185, v186
	v_cvt_pk_bf16_f32 v95, v187, v194
	s_waitcnt lgkmcnt(8)
	s_nop 0
	v_mfma_f32_32x32x16_bf16 v[18:33], v[64:67], v[92:95], v[18:33]
	v_max3_f32 v51, v51, v123, v124
	v_max3_f32 v51, v51, v125, v126
	v_add_f32_e32 v50, v176, v177
	v_add_f32_e32 v50, v50, v178
	v_add_f32_e32 v50, v50, v179
	s_nop 0
	v_mfma_f32_32x32x16_bf16 v[2:17], v[60:63], v[92:95], v[2:17]
	v_cvt_pk_bf16_f32 v64, v195, v196
	v_cvt_pk_bf16_f32 v65, v197, v198
	v_cvt_pk_bf16_f32 v66, v146, v147
	v_cvt_pk_bf16_f32 v67, v148, v149
	v_max3_f32 v51, v51, v127, v128
	v_max3_f32 v51, v51, v129, v130
	v_add_f32_e32 v50, v50, v185
	v_add_f32_e32 v50, v50, v186
	v_add_f32_e32 v50, v50, v187
	v_add_f32_e32 v50, v50, v194
	s_waitcnt lgkmcnt(7)
	v_mfma_f32_32x32x16_bf16 v[18:33], v[68:71], v[64:67], v[18:33]
	v_max3_f32 v51, v51, v131, v132
	v_max3_f32 v51, v51, v133, v134
	v_add_f32_e32 v50, v50, v195
	v_add_f32_e32 v50, v50, v196
	v_add_f32_e32 v50, v50, v197
	v_add_f32_e32 v50, v50, v198
	s_waitcnt lgkmcnt(6)
	v_mfma_f32_32x32x16_bf16 v[2:17], v[72:75], v[64:67], v[2:17]
	v_cvt_pk_bf16_f32 v60, v150, v151
	v_cvt_pk_bf16_f32 v61, v152, v153
	v_cvt_pk_bf16_f32 v62, v199, v200
	v_cvt_pk_bf16_f32 v63, v201, v202
	v_max3_f32 v51, v51, v135, v136
	v_max3_f32 v51, v51, v137, v106
	v_add_f32_e32 v50, v50, v146
	v_add_f32_e32 v50, v50, v147
	v_add_f32_e32 v50, v50, v148
	v_add_f32_e32 v50, v50, v149
	s_waitcnt lgkmcnt(5)
	v_mfma_f32_32x32x16_bf16 v[18:33], v[76:79], v[60:63], v[18:33]
	v_max3_f32 v51, v51, v107, v108
	v_max3_f32 v51, v51, v109, v110
	v_add_f32_e32 v50, v50, v150
	v_add_f32_e32 v50, v50, v151
	v_add_f32_e32 v50, v50, v152
	v_add_f32_e32 v50, v50, v153
	s_waitcnt lgkmcnt(4)
	v_mfma_f32_32x32x16_bf16 v[2:17], v[80:83], v[60:63], v[2:17]
	v_cvt_pk_bf16_f32 v64, v203, v204
	v_cvt_pk_bf16_f32 v65, v205, v206
	v_cvt_pk_bf16_f32 v66, v207, v208
	v_cvt_pk_bf16_f32 v67, v209, v210
	v_max3_f32 v51, v51, v111, v112
	v_max3_f32 v51, v51, v113, v114
	v_add_f32_e32 v50, v50, v199
	v_add_f32_e32 v50, v50, v200
	v_add_f32_e32 v50, v50, v201
	v_add_f32_e32 v50, v50, v202
	s_waitcnt lgkmcnt(3)
	v_mfma_f32_32x32x16_bf16 v[18:33], v[84:87], v[64:67], v[18:33]
	v_max3_f32 v51, v51, v115, v116
	v_max3_f32 v51, v51, v117, v118
	v_add_f32_e32 v50, v50, v203
	v_add_f32_e32 v50, v50, v204
	v_add_f32_e32 v50, v50, v205
	v_add_f32_e32 v50, v50, v206
	s_waitcnt lgkmcnt(2)
	v_mfma_f32_32x32x16_bf16 v[2:17], v[88:91], v[64:67], v[2:17]
	v_max3_f32 v51, v51, v119, v120
	v_max3_f32 v51, v51, v121, v121
	v_add_f32_e32 v50, v50, v207
	v_add_f32_e32 v50, v50, v208
	v_add_f32_e32 v50, v50, v209
	v_add_f32_e32 v50, v50, v210
	s_setprio 0
	ds_read_b128 v[146:149], v165 offset:9248
	ds_read_b128 v[60:63], v165 offset:13856
	v_add_f32_e32 v50, v1, v50
	v_mov_b32_e32 v1, v51
	s_nop 1
	v_permlane32_swap_b32_e32 v51, v1
	v_max_f32_e32 v1, v1, v1
	v_max_f32_e32 v51, v51, v51
	v_max_f32_e32 v1, v51, v1
	v_cmp_lt_f32_e32 vcc, s52, v1
	s_cbranch_vccz .LBB0_643
	v_max_f32_e32 v1, v1, v1
	v_max_f32_e32 v68, 0, v1
	v_add_f32_e32 v183, v183, v68
	v_xor_b32_e32 v34, 0x80000000, v183
	v_pk_add_f32 v[122:123], v[122:123], v[68:69] op_sel_hi:[1,0] neg_lo:[0,1] neg_hi:[0,1]
	v_pk_add_f32 v[106:107], v[106:107], v[68:69] op_sel_hi:[1,0] neg_lo:[0,1] neg_hi:[0,1]
	v_pk_add_f32 v[124:125], v[124:125], v[68:69] op_sel_hi:[1,0] neg_lo:[0,1] neg_hi:[0,1]
	v_pk_add_f32 v[108:109], v[108:109], v[68:69] op_sel_hi:[1,0] neg_lo:[0,1] neg_hi:[0,1]
	v_pk_add_f32 v[126:127], v[126:127], v[68:69] op_sel_hi:[1,0] neg_lo:[0,1] neg_hi:[0,1]
	v_pk_add_f32 v[110:111], v[110:111], v[68:69] op_sel_hi:[1,0] neg_lo:[0,1] neg_hi:[0,1]
	v_pk_add_f32 v[128:129], v[128:129], v[68:69] op_sel_hi:[1,0] neg_lo:[0,1] neg_hi:[0,1]
	v_pk_add_f32 v[112:113], v[112:113], v[68:69] op_sel_hi:[1,0] neg_lo:[0,1] neg_hi:[0,1]
	v_pk_add_f32 v[130:131], v[130:131], v[68:69] op_sel_hi:[1,0] neg_lo:[0,1] neg_hi:[0,1]
	v_pk_add_f32 v[114:115], v[114:115], v[68:69] op_sel_hi:[1,0] neg_lo:[0,1] neg_hi:[0,1]
	v_pk_add_f32 v[132:133], v[132:133], v[68:69] op_sel_hi:[1,0] neg_lo:[0,1] neg_hi:[0,1]
	v_pk_add_f32 v[116:117], v[116:117], v[68:69] op_sel_hi:[1,0] neg_lo:[0,1] neg_hi:[0,1]
	v_pk_add_f32 v[134:135], v[134:135], v[68:69] op_sel_hi:[1,0] neg_lo:[0,1] neg_hi:[0,1]
	v_pk_add_f32 v[118:119], v[118:119], v[68:69] op_sel_hi:[1,0] neg_lo:[0,1] neg_hi:[0,1]
	v_pk_add_f32 v[136:137], v[136:137], v[68:69] op_sel_hi:[1,0] neg_lo:[0,1] neg_hi:[0,1]
	v_pk_add_f32 v[120:121], v[120:121], v[68:69] op_sel_hi:[1,0] neg_lo:[0,1] neg_hi:[0,1]
	v_exp_f32_e64 v68, -v68
	v_mov_b32_e32 v35, v34
	v_mov_b32_e32 v36, v34
	v_mov_b32_e32 v37, v34
	v_mov_b32_e32 v38, v34
	v_mov_b32_e32 v39, v34
	v_mov_b32_e32 v40, v34
	v_mov_b32_e32 v41, v34
	v_mov_b32_e32 v42, v34
	v_mov_b32_e32 v43, v34
	v_mov_b32_e32 v44, v34
	v_mov_b32_e32 v45, v34
	v_mov_b32_e32 v46, v34
	v_mov_b32_e32 v47, v34
	v_mov_b32_e32 v48, v34
	v_mov_b32_e32 v49, v34
	s_nop 11
	v_pk_mul_f32 v[32:33], v[32:33], v[68:69] op_sel_hi:[1,0]
	v_pk_mul_f32 v[30:31], v[30:31], v[68:69] op_sel_hi:[1,0]
	v_pk_mul_f32 v[28:29], v[28:29], v[68:69] op_sel_hi:[1,0]
	v_pk_mul_f32 v[26:27], v[26:27], v[68:69] op_sel_hi:[1,0]
	v_pk_mul_f32 v[24:25], v[24:25], v[68:69] op_sel_hi:[1,0]
	v_pk_mul_f32 v[22:23], v[22:23], v[68:69] op_sel_hi:[1,0]
	v_pk_mul_f32 v[20:21], v[20:21], v[68:69] op_sel_hi:[1,0]
	v_pk_mul_f32 v[18:19], v[18:19], v[68:69] op_sel_hi:[1,0]
	v_pk_mul_f32 v[16:17], v[16:17], v[68:69] op_sel_hi:[1,0]
	v_pk_mul_f32 v[14:15], v[14:15], v[68:69] op_sel_hi:[1,0]
	v_pk_mul_f32 v[12:13], v[12:13], v[68:69] op_sel_hi:[1,0]
	v_pk_mul_f32 v[10:11], v[10:11], v[68:69] op_sel_hi:[1,0]
	v_pk_mul_f32 v[8:9], v[8:9], v[68:69] op_sel_hi:[1,0]
	v_pk_mul_f32 v[6:7], v[6:7], v[68:69] op_sel_hi:[1,0]
	v_pk_mul_f32 v[4:5], v[4:5], v[68:69] op_sel_hi:[1,0]
	v_pk_mul_f32 v[2:3], v[2:3], v[68:69] op_sel_hi:[1,0]
	v_mul_f32_e32 v50, v50, v68

.LBB0_661:
	s_add_i32 s26, s13, -7
	s_lshl_b32 s92, s26, 13
	s_add_u32 vcc_lo, s100, s92
	s_addc_u32 vcc_hi, s101, 0
	global_load_dwordx4 v[2:5], v248, vcc
	s_add_i32 s26, s13, -8
	s_lshl_b32 s92, s26, 7
	s_add_u32 vcc_lo, s98, s92
	s_addc_u32 vcc_hi, s99, 0
	global_load_dwordx4 v[6:9], v249, vcc
	s_mul_i32 s28, s27, 0x2400
	s_add_i32 s26, s13, -7
	s_add_i32 s29, s28, 0xffffdc00
	s_cmp_lg_u32 s27, 0
	s_cselect_b32 s29, s29, 0x9000
	v_add_u32_e32 v1, s29, v195
	ds_read_b128 v[10:13], v1 offset:36864
	ds_read_b128 v[66:69], v1 offset:36896
	ds_read_b128 v[70:73], v1 offset:41472
	ds_read_b128 v[74:77], v1 offset:41504
	ds_read_b128 v[128:131], v1 offset:36928
	ds_read_b128 v[132:135], v1 offset:36960
	ds_read_b128 v[148:151], v1 offset:41536
	ds_read_b128 v[160:163], v1 offset:41568
	s_setprio 3
	v_cvt_pk_bf16_f32 v210, v116, v117
	v_cvt_pk_bf16_f32 v211, v118, v119
	v_cvt_pk_bf16_f32 v212, v112, v113
	v_cvt_pk_bf16_f32 v213, v114, v115
	s_waitcnt lgkmcnt(7)
	s_nop 0
	v_mfma_f32_32x32x16_bf16 v[16:31], v[10:13], v[210:213], v[16:31]
	v_add_f32_e32 v1, v116, v117
	v_add_f32_e32 v1, v1, v118
	v_add_f32_e32 v1, v1, v119
	s_waitcnt lgkmcnt(5)
	v_mfma_f32_32x32x16_bf16 v[32:47], v[70:73], v[210:213], v[32:47]
	v_cvt_pk_bf16_f32 v10, v187, v186
	v_cvt_pk_bf16_f32 v11, v185, v184
	v_cvt_pk_bf16_f32 v12, v147, v146
	v_cvt_pk_bf16_f32 v13, v145, v144
	v_add_f32_e32 v1, v1, v112
	v_add_f32_e32 v1, v1, v113
	v_add_f32_e32 v1, v1, v114
	v_add_f32_e32 v1, v1, v115
	s_nop 0
	v_mfma_f32_32x32x16_bf16 v[16:31], v[66:69], v[10:13], v[16:31]
	v_add_f32_e32 v1, v1, v187
	v_add_f32_e32 v1, v1, v186
	v_add_f32_e32 v1, v1, v185
	v_add_f32_e32 v1, v1, v184
	s_waitcnt lgkmcnt(4)
	v_mfma_f32_32x32x16_bf16 v[32:47], v[74:77], v[10:13], v[32:47]
	v_cvt_pk_bf16_f32 v66, v143, v142
	v_cvt_pk_bf16_f32 v67, v141, v140
	v_cvt_pk_bf16_f32 v68, v139, v138
	v_cvt_pk_bf16_f32 v69, v137, v136
	v_add_f32_e32 v1, v1, v147
	v_add_f32_e32 v1, v1, v146
	v_add_f32_e32 v1, v1, v145
	v_add_f32_e32 v1, v1, v144
	s_waitcnt lgkmcnt(3)
	v_mfma_f32_32x32x16_bf16 v[16:31], v[128:131], v[66:69], v[16:31]
	v_add_f32_e32 v1, v1, v143
	v_add_f32_e32 v1, v1, v142
	v_add_f32_e32 v1, v1, v141
	v_add_f32_e32 v1, v1, v140
	s_waitcnt lgkmcnt(1)
	v_mfma_f32_32x32x16_bf16 v[32:47], v[148:151], v[66:69], v[32:47]
	v_cvt_pk_bf16_f32 v10, v123, v122
	v_cvt_pk_bf16_f32 v11, v121, v120
	v_cvt_pk_bf16_f32 v12, v127, v126
	v_cvt_pk_bf16_f32 v13, v125, v124
	v_add_f32_e32 v1, v1, v139
	v_add_f32_e32 v1, v1, v138
	v_add_f32_e32 v1, v1, v137
	v_add_f32_e32 v1, v1, v136
	s_nop 0
	v_mfma_f32_32x32x16_bf16 v[16:31], v[132:135], v[10:13], v[16:31]
	v_add_f32_e32 v1, v1, v123
	v_add_f32_e32 v1, v1, v122
	v_add_f32_e32 v1, v1, v121
	v_add_f32_e32 v1, v1, v120
	s_waitcnt lgkmcnt(0)
	v_mfma_f32_32x32x16_bf16 v[32:47], v[160:163], v[10:13], v[32:47]
	v_add_f32_e32 v1, v1, v127
	v_add_f32_e32 v1, v1, v126
	v_add_f32_e32 v1, v1, v125
	v_add_f32_e32 v1, v1, v124
	s_setprio 2
	s_waitcnt lgkmcnt(0)
	s_barrier
	ds_read_b128 v[240:243], v195 offset:18432
	ds_read_b128 v[244:247], v195 offset:23040
	ds_read_b128 v[66:69], v195 offset:18464
	ds_read_b128 v[74:77], v195 offset:23072
	ds_read_b128 v[144:147], v195 offset:18496
	ds_read_b128 v[148:151], v195 offset:18528
	ds_read_b128 v[160:163], v195 offset:23104
	ds_read_b128 v[184:187], v195 offset:23136
	s_waitcnt lgkmcnt(6)
	v_mfma_f32_32x32x16_bf16 v[128:143], v[240:243], v[180:183], v[48:63]
	v_exp_f32_e32 v166, v96
	v_exp_f32_e32 v167, v97
	v_exp_f32_e32 v210, v98
	v_exp_f32_e32 v211, v99
	s_waitcnt lgkmcnt(5)
	v_mfma_f32_32x32x16_bf16 v[112:127], v[244:247], v[180:183], v[48:63]
	v_exp_f32_e32 v212, v100
	v_exp_f32_e32 v213, v101
	v_exp_f32_e32 v214, v102
	v_exp_f32_e32 v215, v103
	v_mfma_f32_32x32x16_bf16 v[128:143], v[66:69], v[176:179], v[128:143]
	v_exp_f32_e32 v100, v104
	v_exp_f32_e32 v101, v105
	v_exp_f32_e32 v102, v106
	v_exp_f32_e32 v103, v107
	s_waitcnt lgkmcnt(4)
	v_mfma_f32_32x32x16_bf16 v[112:127], v[74:77], v[176:179], v[112:127]
	v_exp_f32_e32 v104, v108
	v_exp_f32_e32 v105, v109
	v_exp_f32_e32 v106, v110
	v_exp_f32_e32 v107, v111
	s_waitcnt lgkmcnt(3)
	v_mfma_f32_32x32x16_bf16 v[128:143], v[144:147], v[172:175], v[128:143]
	v_exp_f32_e32 v108, v80
	v_exp_f32_e32 v109, v81
	v_exp_f32_e32 v110, v82
	v_exp_f32_e32 v111, v83
	s_waitcnt lgkmcnt(1)
	v_mfma_f32_32x32x16_bf16 v[112:127], v[160:163], v[172:175], v[112:127]
	v_exp_f32_e32 v144, v84
	v_exp_f32_e32 v145, v85
	v_exp_f32_e32 v146, v86
	v_exp_f32_e32 v147, v87
	v_mfma_f32_32x32x16_bf16 v[128:143], v[148:151], v[168:171], v[128:143]
	v_exp_f32_e32 v216, v88
	v_exp_f32_e32 v217, v89
	v_exp_f32_e32 v218, v90
	v_exp_f32_e32 v219, v91
	s_waitcnt lgkmcnt(0)
	v_mfma_f32_32x32x16_bf16 v[112:127], v[184:187], v[168:171], v[112:127]
	v_exp_f32_e32 v148, v92
	v_exp_f32_e32 v149, v93
	v_exp_f32_e32 v150, v94
	v_exp_f32_e32 v151, v95
	v_add_f32_e32 v1, v64, v1
	v_add_u32_e32 v92, s28, v195
	ds_read_b128 v[240:243], v195 offset:27648
	ds_read_b128 v[244:247], v195 offset:32256
	ds_read_b128 v[64:67], v92 offset:41472
	ds_read_b128 v[68:71], v92 offset:36864
	ds_read_b128 v[72:75], v92 offset:36896
	ds_read_b128 v[76:79], v92 offset:41504
	ds_read_b128 v[80:83], v92 offset:36928
	ds_read_b128 v[84:87], v92 offset:41536
	ds_read_b128 v[88:91], v92 offset:36960
	ds_read_b128 v[92:95], v92 offset:41568
	s_cmp_gt_i32 s27, 2
	s_cselect_b32 s29, -3, 2
	s_add_i32 s29, s29, s27
	s_add_i32 s28, s13, -6
	s_mulk_i32 s29, 0x2400
	s_min_u32 s28, s28, s12
	v_add_u32_e32 v10, s29, v208
	s_min_u32 s26, s26, s12
	s_lshl_b32 s92, s28, 13
	s_waitcnt vmcnt(3)
	ds_write_b128 v208, v[152:155]
	s_waitcnt vmcnt(2)
	ds_write_b128 v10, v[156:159] offset:36864
	s_add_u32 vcc_lo, s100, s92
	s_addc_u32 vcc_hi, s101, 0
	global_load_dwordx4 v[10:13], v248, vcc
	s_lshl_b32 s92, s26, 7
	s_add_u32 vcc_lo, s98, s92
	s_addc_u32 vcc_hi, s99, 0
	global_load_dwordx4 v[160:163], v249, vcc
	s_add_i32 s29, s27, 1
	s_setprio 1
	v_cvt_pk_bf16_f32 v96, v166, v167
	v_cvt_pk_bf16_f32 v97, v210, v211
	v_cvt_pk_bf16_f32 v98, v212, v213
	v_cvt_pk_bf16_f32 v99, v214, v215
	s_waitcnt lgkmcnt(8)
	s_nop 0
	v_mfma_f32_32x32x16_bf16 v[16:31], v[68:71], v[96:99], v[16:31]
	v_add_f32_e32 v184, v166, v167
	v_add_f32_e32 v184, v184, v210
	v_add_f32_e32 v184, v184, v211
	s_nop 0
	v_mfma_f32_32x32x16_bf16 v[32:47], v[64:67], v[96:99], v[32:47]
	v_cvt_pk_bf16_f32 v68, v100, v101
	v_cvt_pk_bf16_f32 v69, v102, v103
	v_cvt_pk_bf16_f32 v70, v104, v105
	v_cvt_pk_bf16_f32 v71, v106, v107
	v_add_f32_e32 v184, v184, v212
	v_add_f32_e32 v184, v184, v213
	v_add_f32_e32 v184, v184, v214
	v_add_f32_e32 v184, v184, v215
	s_waitcnt lgkmcnt(7)
	v_mfma_f32_32x32x16_bf16 v[16:31], v[72:75], v[68:71], v[16:31]
	v_add_f32_e32 v184, v184, v100
	v_add_f32_e32 v184, v184, v101
	v_add_f32_e32 v184, v184, v102
	v_add_f32_e32 v184, v184, v103
	s_waitcnt lgkmcnt(6)
	v_mfma_f32_32x32x16_bf16 v[32:47], v[76:79], v[68:71], v[32:47]
	v_cvt_pk_bf16_f32 v64, v108, v109
	v_cvt_pk_bf16_f32 v65, v110, v111
	v_cvt_pk_bf16_f32 v66, v144, v145
	v_cvt_pk_bf16_f32 v67, v146, v147
	v_add_f32_e32 v184, v184, v104
	v_add_f32_e32 v184, v184, v105
	v_add_f32_e32 v184, v184, v106
	v_add_f32_e32 v184, v184, v107
	s_waitcnt lgkmcnt(5)
	v_mfma_f32_32x32x16_bf16 v[16:31], v[80:83], v[64:67], v[16:31]
	v_add_f32_e32 v184, v184, v108
	v_add_f32_e32 v184, v184, v109
	v_add_f32_e32 v184, v184, v110
	v_add_f32_e32 v184, v184, v111
	s_waitcnt lgkmcnt(4)
	v_mfma_f32_32x32x16_bf16 v[32:47], v[84:87], v[64:67], v[32:47]
	v_cvt_pk_bf16_f32 v68, v216, v217
	v_cvt_pk_bf16_f32 v69, v218, v219
	v_cvt_pk_bf16_f32 v70, v148, v149
	v_cvt_pk_bf16_f32 v71, v150, v151
	v_add_f32_e32 v184, v184, v144
	v_add_f32_e32 v184, v184, v145
	v_add_f32_e32 v184, v184, v146
	v_add_f32_e32 v184, v184, v147
	s_waitcnt lgkmcnt(3)
	v_mfma_f32_32x32x16_bf16 v[16:31], v[88:91], v[68:71], v[16:31]
	v_add_f32_e32 v184, v184, v216
	v_add_f32_e32 v184, v184, v217
	v_add_f32_e32 v184, v184, v218
	v_add_f32_e32 v184, v184, v219
	s_waitcnt lgkmcnt(2)
	v_mfma_f32_32x32x16_bf16 v[32:47], v[92:95], v[68:71], v[32:47]
	v_add_f32_e32 v184, v184, v148
	v_add_f32_e32 v184, v184, v149
	v_add_f32_e32 v184, v184, v150
	v_add_f32_e32 v184, v184, v151
	s_setprio 0
	ds_read_b128 v[68:71], v195 offset:27680
	ds_read_b128 v[76:79], v195 offset:32288
	ds_read_b128 v[80:83], v195 offset:27712
	ds_read_b128 v[84:87], v195 offset:27744
	ds_read_b128 v[88:91], v195 offset:32320
	ds_read_b128 v[92:95], v195 offset:32352
	s_cmp_lg_u32 s27, 4
	s_cselect_b32 s26, s29, 0
	s_waitcnt lgkmcnt(6)
	v_mfma_f32_32x32x16_bf16 v[144:159], v[240:243], v[180:183], v[48:63]
	v_exp_f32_e32 v166, v128
	v_exp_f32_e32 v167, v129
	v_exp_f32_e32 v185, v130
	v_exp_f32_e32 v186, v131
	s_waitcnt lgkmcnt(5)
	v_mfma_f32_32x32x16_bf16 v[96:111], v[244:247], v[180:183], v[48:63]
	v_exp_f32_e32 v128, v132
	v_exp_f32_e32 v129, v133
	v_exp_f32_e32 v130, v134
	v_exp_f32_e32 v131, v135
	v_mfma_f32_32x32x16_bf16 v[144:159], v[68:71], v[176:179], v[144:159]
	v_exp_f32_e32 v132, v136
	v_exp_f32_e32 v133, v137
	v_exp_f32_e32 v134, v138
	v_exp_f32_e32 v135, v139
	s_waitcnt lgkmcnt(4)
	v_mfma_f32_32x32x16_bf16 v[96:111], v[76:79], v[176:179], v[96:111]
	v_exp_f32_e32 v136, v140
	v_exp_f32_e32 v137, v141
	v_exp_f32_e32 v138, v142
	v_exp_f32_e32 v139, v143
	s_waitcnt lgkmcnt(3)
	v_mfma_f32_32x32x16_bf16 v[144:159], v[80:83], v[172:175], v[144:159]
	v_exp_f32_e32 v140, v112
	v_exp_f32_e32 v141, v113
	v_exp_f32_e32 v142, v114
	v_exp_f32_e32 v143, v115
	s_waitcnt lgkmcnt(1)
	v_mfma_f32_32x32x16_bf16 v[96:111], v[88:91], v[172:175], v[96:111]
	v_exp_f32_e32 v187, v116
	v_exp_f32_e32 v210, v117
	v_exp_f32_e32 v211, v118
	v_exp_f32_e32 v212, v119
	v_mfma_f32_32x32x16_bf16 v[144:159], v[84:87], v[168:171], v[144:159]
	v_exp_f32_e32 v116, v120
	v_exp_f32_e32 v117, v121
	v_exp_f32_e32 v118, v122
	v_exp_f32_e32 v119, v123
	s_waitcnt lgkmcnt(0)
	v_mfma_f32_32x32x16_bf16 v[96:111], v[92:95], v[168:171], v[96:111]
	v_exp_f32_e32 v120, v124
	v_exp_f32_e32 v121, v125
	v_exp_f32_e32 v122, v126
	v_exp_f32_e32 v123, v127
	s_cmp_gt_i32 s26, 2
	s_cselect_b32 s27, -3, 2
	s_add_i32 s27, s27, s26
	s_mulk_i32 s27, 0x2400
	s_waitcnt vmcnt(3)
	ds_write_b128 v208, v[2:5] offset:9216
	v_add_u32_e32 v2, s27, v208
	s_add_i32 s27, s26, 1
	s_cmp_lg_u32 s26, 4
	s_cselect_b32 s26, s27, 0
	s_add_i32 s27, s13, -5
	s_min_u32 s27, s27, s12
	s_lshl_b32 s92, s27, 13
	s_waitcnt vmcnt(2)
	ds_write_b128 v2, v[6:9] offset:36864
	s_add_u32 vcc_lo, s100, s92
	s_addc_u32 vcc_hi, s101, 0
	global_load_dwordx4 v[6:9], v248, vcc
	s_lshl_b32 s92, s28, 7
	s_add_u32 vcc_lo, s98, s92
	s_addc_u32 vcc_hi, s99, 0
	global_load_dwordx4 v[2:5], v249, vcc
	s_nop 0
	s_mul_i32 s28, s26, 0x2400
	s_add_i32 s29, s28, 0xffffdc00
	s_cmp_lg_u32 s26, 0
	s_cselect_b32 s29, s29, 0x9000
	v_add_u32_e32 v92, s29, v195
	ds_read_b128 v[64:67], v92 offset:36864
	ds_read_b128 v[68:71], v92 offset:36896
	ds_read_b128 v[72:75], v92 offset:41472
	ds_read_b128 v[76:79], v92 offset:41504
	ds_read_b128 v[80:83], v92 offset:36928
	ds_read_b128 v[84:87], v92 offset:36960
	ds_read_b128 v[88:91], v92 offset:41536
	ds_read_b128 v[92:95], v92 offset:41568
	s_setprio 3
	v_cvt_pk_bf16_f32 v112, v166, v167
	v_cvt_pk_bf16_f32 v113, v185, v186
	v_cvt_pk_bf16_f32 v114, v128, v129
	v_cvt_pk_bf16_f32 v115, v130, v131
	s_waitcnt lgkmcnt(7)
	s_nop 0
	v_mfma_f32_32x32x16_bf16 v[16:31], v[64:67], v[112:115], v[16:31]
	v_add_f32_e32 v213, v166, v167
	v_add_f32_e32 v213, v213, v185
	v_add_f32_e32 v213, v213, v186
	s_waitcnt lgkmcnt(5)
	v_mfma_f32_32x32x16_bf16 v[32:47], v[72:75], v[112:115], v[32:47]
	v_cvt_pk_bf16_f32 v64, v132, v133
	v_cvt_pk_bf16_f32 v65, v134, v135
	v_cvt_pk_bf16_f32 v66, v136, v137
	v_cvt_pk_bf16_f32 v67, v138, v139
	v_add_f32_e32 v213, v213, v128
	v_add_f32_e32 v213, v213, v129
	v_add_f32_e32 v213, v213, v130
	v_add_f32_e32 v213, v213, v131
	s_nop 0
	v_mfma_f32_32x32x16_bf16 v[16:31], v[68:71], v[64:67], v[16:31]
	v_add_f32_e32 v213, v213, v132
	v_add_f32_e32 v213, v213, v133
	v_add_f32_e32 v213, v213, v134
	v_add_f32_e32 v213, v213, v135
	s_waitcnt lgkmcnt(4)
	v_mfma_f32_32x32x16_bf16 v[32:47], v[76:79], v[64:67], v[32:47]
	v_cvt_pk_bf16_f32 v68, v140, v141
	v_cvt_pk_bf16_f32 v69, v142, v143
	v_cvt_pk_bf16_f32 v70, v187, v210
	v_cvt_pk_bf16_f32 v71, v211, v212
	v_add_f32_e32 v213, v213, v136
	v_add_f32_e32 v213, v213, v137
	v_add_f32_e32 v213, v213, v138
	v_add_f32_e32 v213, v213, v139
	s_waitcnt lgkmcnt(3)
	v_mfma_f32_32x32x16_bf16 v[16:31], v[80:83], v[68:71], v[16:31]
	v_add_f32_e32 v213, v213, v140
	v_add_f32_e32 v213, v213, v141
	v_add_f32_e32 v213, v213, v142
	v_add_f32_e32 v213, v213, v143
	s_waitcnt lgkmcnt(1)
	v_mfma_f32_32x32x16_bf16 v[32:47], v[88:91], v[68:71], v[32:47]
	v_cvt_pk_bf16_f32 v64, v116, v117
	v_cvt_pk_bf16_f32 v65, v118, v119
	v_cvt_pk_bf16_f32 v66, v120, v121
	v_cvt_pk_bf16_f32 v67, v122, v123
	v_add_f32_e32 v213, v213, v187
	v_add_f32_e32 v213, v213, v210
	v_add_f32_e32 v213, v213, v211
	v_add_f32_e32 v213, v213, v212
	s_nop 0
	v_mfma_f32_32x32x16_bf16 v[16:31], v[84:87], v[64:67], v[16:31]
	v_add_f32_e32 v213, v213, v116
	v_add_f32_e32 v213, v213, v117
	v_add_f32_e32 v213, v213, v118
	v_add_f32_e32 v213, v213, v119
	s_waitcnt lgkmcnt(0)
	v_mfma_f32_32x32x16_bf16 v[32:47], v[92:95], v[64:67], v[32:47]
	v_add_f32_e32 v213, v213, v120
	v_add_f32_e32 v213, v213, v121
	v_add_f32_e32 v213, v213, v122
	v_add_f32_e32 v213, v213, v123
	s_setprio 2
	s_waitcnt lgkmcnt(0)
	s_barrier
	ds_read_b128 v[240:243], v195
	ds_read_b128 v[244:247], v195 offset:4608
	ds_read_b128 v[116:119], v195 offset:32
	ds_read_b128 v[120:123], v195 offset:4640
	ds_read_b128 v[124:127], v195 offset:64
	ds_read_b128 v[128:131], v195 offset:4672
	ds_read_b128 v[132:135], v195 offset:96
	ds_read_b128 v[136:139], v195 offset:4704
	v_add_f32_e32 v1, v1, v184
	s_waitcnt lgkmcnt(6)
	v_mfma_f32_32x32x16_bf16 v[80:95], v[240:243], v[180:183], v[48:63]
	v_exp_f32_e32 v140, v144
	v_exp_f32_e32 v141, v145
	v_exp_f32_e32 v142, v146
	v_exp_f32_e32 v143, v147
	v_mfma_f32_32x32x16_bf16 v[64:79], v[244:247], v[180:183], v[48:63]
	v_exp_f32_e32 v144, v148
	v_exp_f32_e32 v145, v149
	v_exp_f32_e32 v146, v150
	v_exp_f32_e32 v147, v151
	s_waitcnt lgkmcnt(5)
	v_mfma_f32_32x32x16_bf16 v[80:95], v[116:119], v[176:179], v[80:95]
	v_exp_f32_e32 v148, v152
	v_exp_f32_e32 v149, v153
	v_exp_f32_e32 v150, v154
	v_exp_f32_e32 v151, v155
	s_waitcnt lgkmcnt(4)
	v_mfma_f32_32x32x16_bf16 v[64:79], v[120:123], v[176:179], v[64:79]
	v_exp_f32_e32 v152, v156
	v_exp_f32_e32 v153, v157
	v_exp_f32_e32 v154, v158
	v_exp_f32_e32 v155, v159
	s_waitcnt lgkmcnt(3)
	v_mfma_f32_32x32x16_bf16 v[80:95], v[124:127], v[172:175], v[80:95]
	v_exp_f32_e32 v156, v96
	v_exp_f32_e32 v157, v97
	v_exp_f32_e32 v158, v98
	v_exp_f32_e32 v159, v99
	s_waitcnt lgkmcnt(2)
	v_mfma_f32_32x32x16_bf16 v[64:79], v[128:131], v[172:175], v[64:79]
	v_exp_f32_e32 v166, v100
	v_exp_f32_e32 v167, v101
	v_exp_f32_e32 v184, v102
	v_exp_f32_e32 v185, v103
	s_waitcnt lgkmcnt(1)
	v_mfma_f32_32x32x16_bf16 v[80:95], v[132:135], v[168:171], v[80:95]
	v_exp_f32_e32 v186, v104
	v_exp_f32_e32 v187, v105
	v_exp_f32_e32 v210, v106
	v_exp_f32_e32 v211, v107
	s_waitcnt lgkmcnt(0)
	v_mfma_f32_32x32x16_bf16 v[64:79], v[136:139], v[168:171], v[64:79]
	v_exp_f32_e32 v212, v108
	v_exp_f32_e32 v214, v109
	v_exp_f32_e32 v215, v110
	v_exp_f32_e32 v216, v111
	v_add_u32_e32 v124, s28, v195
	ds_read_b128 v[240:243], v195 offset:9216
	ds_read_b128 v[244:247], v195 offset:13824
	ds_read_b128 v[96:99], v124 offset:41472
	ds_read_b128 v[100:103], v124 offset:36864
	ds_read_b128 v[104:107], v124 offset:36896
	ds_read_b128 v[108:111], v124 offset:41504
	ds_read_b128 v[112:115], v124 offset:36928
	ds_read_b128 v[116:119], v124 offset:41536
	ds_read_b128 v[120:123], v124 offset:36960
	ds_read_b128 v[124:127], v124 offset:41568
	s_cmp_gt_i32 s26, 2
	s_cselect_b32 s29, -3, 2
	s_add_i32 s29, s29, s26
	s_mulk_i32 s29, 0x2400
	s_waitcnt vmcnt(3)
	ds_write_b128 v208, v[10:13] offset:18432
	v_add_u32_e32 v10, s29, v208
	s_mov_b32 s29, 0x1da90000
	s_waitcnt vmcnt(2)
	ds_write_b128 v10, v[160:163] offset:36864
	s_add_i32 s92, s13, -4
	s_lshl_b32 s92, s92, 13
	s_add_u32 vcc_lo, s100, s92
	s_addc_u32 vcc_hi, s101, 0
	global_load_dwordx4 v[128:131], v248, vcc
	s_lshl_b32 s92, s27, 7
	s_add_u32 vcc_lo, s98, s92
	s_addc_u32 vcc_hi, s99, 0
	global_load_dwordx4 v[10:13], v249, vcc
	v_add_f32_e32 v1, v1, v213
	s_add_i32 s28, s26, 1
	s_setprio 1
	v_cvt_pk_bf16_f32 v132, v140, v141
	v_cvt_pk_bf16_f32 v133, v142, v143
	v_cvt_pk_bf16_f32 v134, v144, v145
	v_cvt_pk_bf16_f32 v135, v146, v147
	s_waitcnt lgkmcnt(8)
	s_nop 0
	v_mfma_f32_32x32x16_bf16 v[16:31], v[100:103], v[132:135], v[16:31]
	v_add_f32_e32 v160, v140, v141
	v_add_f32_e32 v160, v160, v142
	v_add_f32_e32 v160, v160, v143
	s_nop 0
	v_mfma_f32_32x32x16_bf16 v[32:47], v[96:99], v[132:135], v[32:47]
	v_cvt_pk_bf16_f32 v100, v148, v149
	v_cvt_pk_bf16_f32 v101, v150, v151
	v_cvt_pk_bf16_f32 v102, v152, v153
	v_cvt_pk_bf16_f32 v103, v154, v155
	v_add_f32_e32 v160, v160, v144
	v_add_f32_e32 v160, v160, v145
	v_add_f32_e32 v160, v160, v146
	v_add_f32_e32 v160, v160, v147
	s_waitcnt lgkmcnt(7)
	v_mfma_f32_32x32x16_bf16 v[16:31], v[104:107], v[100:103], v[16:31]
	v_add_f32_e32 v160, v160, v148
	v_add_f32_e32 v160, v160, v149
	v_add_f32_e32 v160, v160, v150
	v_add_f32_e32 v160, v160, v151
	s_waitcnt lgkmcnt(6)
	v_mfma_f32_32x32x16_bf16 v[32:47], v[108:111], v[100:103], v[32:47]
	v_cvt_pk_bf16_f32 v96, v156, v157
	v_cvt_pk_bf16_f32 v97, v158, v159
	v_cvt_pk_bf16_f32 v98, v166, v167
	v_cvt_pk_bf16_f32 v99, v184, v185
	v_add_f32_e32 v160, v160, v152
	v_add_f32_e32 v160, v160, v153
	v_add_f32_e32 v160, v160, v154
	v_add_f32_e32 v160, v160, v155
	s_waitcnt lgkmcnt(5)
	v_mfma_f32_32x32x16_bf16 v[16:31], v[112:115], v[96:99], v[16:31]
	v_add_f32_e32 v160, v160, v156
	v_add_f32_e32 v160, v160, v157
	v_add_f32_e32 v160, v160, v158
	v_add_f32_e32 v160, v160, v159
	s_waitcnt lgkmcnt(4)
	v_mfma_f32_32x32x16_bf16 v[32:47], v[116:119], v[96:99], v[32:47]
	v_cvt_pk_bf16_f32 v100, v186, v187
	v_cvt_pk_bf16_f32 v101, v210, v211
	v_cvt_pk_bf16_f32 v102, v212, v214
	v_cvt_pk_bf16_f32 v103, v215, v216
	v_add_f32_e32 v160, v160, v166
	v_add_f32_e32 v160, v160, v167
	v_add_f32_e32 v160, v160, v184
	v_add_f32_e32 v160, v160, v185
	s_waitcnt lgkmcnt(3)
	v_mfma_f32_32x32x16_bf16 v[16:31], v[120:123], v[100:103], v[16:31]
	v_add_f32_e32 v160, v160, v186
	v_add_f32_e32 v160, v160, v187
	v_add_f32_e32 v160, v160, v210
	v_add_f32_e32 v160, v160, v211
	s_waitcnt lgkmcnt(2)
	v_mfma_f32_32x32x16_bf16 v[32:47], v[124:127], v[100:103], v[32:47]
	v_add_f32_e32 v160, v160, v212
	v_add_f32_e32 v160, v160, v214
	v_add_f32_e32 v160, v160, v215
	v_add_f32_e32 v160, v160, v216
	s_setprio 0
	ds_read_b128 v[132:135], v195 offset:9248
	ds_read_b128 v[140:143], v195 offset:13856
	ds_read_b128 v[144:147], v195 offset:9280
	ds_read_b128 v[148:151], v195 offset:9312
	ds_read_b128 v[152:155], v195 offset:13888
	ds_read_b128 v[156:159], v195 offset:13920
	s_cmp_lg_u32 s26, 4
	s_cselect_b32 s26, s28, 0
	s_waitcnt lgkmcnt(6)
	v_mfma_f32_32x32x16_bf16 v[112:127], v[240:243], v[180:183], v[48:63]
	v_exp_f32_e32 v161, v80
	v_exp_f32_e32 v162, v81
	v_exp_f32_e32 v163, v82
	v_exp_f32_e32 v164, v83
	s_waitcnt lgkmcnt(5)
	v_mfma_f32_32x32x16_bf16 v[96:111], v[244:247], v[180:183], v[48:63]
	v_exp_f32_e32 v165, v84
	v_exp_f32_e32 v166, v85
	v_exp_f32_e32 v167, v86
	v_exp_f32_e32 v184, v87
	v_mfma_f32_32x32x16_bf16 v[112:127], v[132:135], v[176:179], v[112:127]
	v_exp_f32_e32 v136, v88
	v_exp_f32_e32 v137, v89
	v_exp_f32_e32 v138, v90
	v_exp_f32_e32 v139, v91
	s_waitcnt lgkmcnt(4)
	v_mfma_f32_32x32x16_bf16 v[96:111], v[140:143], v[176:179], v[96:111]
	v_exp_f32_e32 v185, v92
	v_exp_f32_e32 v186, v93
	v_exp_f32_e32 v187, v94
	v_exp_f32_e32 v210, v95
	s_waitcnt lgkmcnt(3)
	v_mfma_f32_32x32x16_bf16 v[112:127], v[144:147], v[172:175], v[112:127]
	v_exp_f32_e32 v140, v64
	v_exp_f32_e32 v141, v65
	v_exp_f32_e32 v142, v66
	v_exp_f32_e32 v143, v67
	s_waitcnt lgkmcnt(1)
	v_mfma_f32_32x32x16_bf16 v[96:111], v[152:155], v[172:175], v[96:111]
	v_exp_f32_e32 v144, v68
	v_exp_f32_e32 v145, v69
	v_exp_f32_e32 v146, v70
	v_exp_f32_e32 v147, v71
	v_mfma_f32_32x32x16_bf16 v[112:127], v[148:151], v[168:171], v[112:127]
	v_exp_f32_e32 v152, v72
	v_exp_f32_e32 v153, v73
	v_exp_f32_e32 v154, v74
	v_exp_f32_e32 v155, v75
	s_waitcnt lgkmcnt(0)
	v_mfma_f32_32x32x16_bf16 v[96:111], v[156:159], v[168:171], v[96:111]
	v_exp_f32_e32 v148, v76
	v_exp_f32_e32 v149, v77
	v_exp_f32_e32 v150, v78
	v_exp_f32_e32 v151, v79
	s_cmp_gt_i32 s26, 2
	s_cselect_b32 s27, -3, 2
	s_add_i32 s27, s27, s26
	s_mulk_i32 s27, 0x2400
	s_waitcnt vmcnt(3)
	ds_write_b128 v208, v[6:9] offset:27648
	v_add_u32_e32 v6, s27, v208
	s_add_i32 s27, s26, 1
	s_cmp_lg_u32 s26, 4
	s_cselect_b32 s27, s27, 0
	s_add_i32 s26, s13, -3
	s_min_u32 s28, s26, s12
	s_lshl_b32 s92, s28, 13
	s_waitcnt vmcnt(2)
	ds_write_b128 v6, v[2:5] offset:36864
	s_add_u32 vcc_lo, s100, s92
	s_addc_u32 vcc_hi, s101, 0
	global_load_dwordx4 v[6:9], v248, vcc
	s_nop 0
	s_add_i32 s92, s13, -4
	s_lshl_b32 s92, s92, 7
	s_add_u32 vcc_lo, s98, s92
	s_addc_u32 vcc_hi, s99, 0
	global_load_dwordx4 v[2:5], v249, vcc
	s_mul_i32 s29, s27, 0x2400
	s_add_i32 s34, s29, 0xffffdc00
	s_cmp_lg_u32 s27, 0
	s_cselect_b32 s34, s34, 0x9000
	v_add_u32_e32 v14, s34, v195
	ds_read_b128 v[64:67], v14 offset:36864
	ds_read_b128 v[68:71], v14 offset:36896
	ds_read_b128 v[72:75], v14 offset:41472
	ds_read_b128 v[76:79], v14 offset:41504
	ds_read_b128 v[80:83], v14 offset:36928
	ds_read_b128 v[84:87], v14 offset:36960
	ds_read_b128 v[88:91], v14 offset:41536
	ds_read_b128 v[92:95], v14 offset:41568
	s_setprio 3
	v_cvt_pk_bf16_f32 v132, v161, v162
	v_cvt_pk_bf16_f32 v133, v163, v164
	v_cvt_pk_bf16_f32 v134, v165, v166
	v_cvt_pk_bf16_f32 v135, v167, v184
	s_waitcnt lgkmcnt(7)
	s_nop 0
	v_mfma_f32_32x32x16_bf16 v[16:31], v[64:67], v[132:135], v[16:31]
	v_add_f32_e32 v14, v161, v162
	v_add_f32_e32 v14, v14, v163
	v_add_f32_e32 v14, v14, v164
	s_waitcnt lgkmcnt(5)
	v_mfma_f32_32x32x16_bf16 v[32:47], v[72:75], v[132:135], v[32:47]
	v_cvt_pk_bf16_f32 v64, v136, v137
	v_cvt_pk_bf16_f32 v65, v138, v139
	v_cvt_pk_bf16_f32 v66, v185, v186
	v_cvt_pk_bf16_f32 v67, v187, v210
	v_add_f32_e32 v14, v14, v165
	v_add_f32_e32 v14, v14, v166
	v_add_f32_e32 v14, v14, v167
	v_add_f32_e32 v14, v14, v184
	s_nop 0
	v_mfma_f32_32x32x16_bf16 v[16:31], v[68:71], v[64:67], v[16:31]
	v_add_f32_e32 v14, v14, v136
	v_add_f32_e32 v14, v14, v137
	v_add_f32_e32 v14, v14, v138
	v_add_f32_e32 v14, v14, v139
	s_waitcnt lgkmcnt(4)
	v_mfma_f32_32x32x16_bf16 v[32:47], v[76:79], v[64:67], v[32:47]
	v_cvt_pk_bf16_f32 v68, v140, v141
	v_cvt_pk_bf16_f32 v69, v142, v143
	v_cvt_pk_bf16_f32 v70, v144, v145
	v_cvt_pk_bf16_f32 v71, v146, v147
	v_add_f32_e32 v14, v14, v185
	v_add_f32_e32 v14, v14, v186
	v_add_f32_e32 v14, v14, v187
	v_add_f32_e32 v14, v14, v210
	s_waitcnt lgkmcnt(3)
	v_mfma_f32_32x32x16_bf16 v[16:31], v[80:83], v[68:71], v[16:31]
	v_add_f32_e32 v14, v14, v140
	v_add_f32_e32 v14, v14, v141
	v_add_f32_e32 v14, v14, v142
	v_add_f32_e32 v14, v14, v143
	s_waitcnt lgkmcnt(1)
	v_mfma_f32_32x32x16_bf16 v[32:47], v[88:91], v[68:71], v[32:47]
	v_cvt_pk_bf16_f32 v64, v152, v153
	v_cvt_pk_bf16_f32 v65, v154, v155
	v_cvt_pk_bf16_f32 v66, v148, v149
	v_cvt_pk_bf16_f32 v67, v150, v151
	v_add_f32_e32 v14, v14, v144
	v_add_f32_e32 v14, v14, v145
	v_add_f32_e32 v14, v14, v146
	v_add_f32_e32 v14, v14, v147
	s_nop 0
	v_mfma_f32_32x32x16_bf16 v[16:31], v[84:87], v[64:67], v[16:31]
	v_add_f32_e32 v14, v14, v152
	v_add_f32_e32 v14, v14, v153
	v_add_f32_e32 v14, v14, v154
	v_add_f32_e32 v14, v14, v155
	s_waitcnt lgkmcnt(0)
	v_mfma_f32_32x32x16_bf16 v[32:47], v[92:95], v[64:67], v[32:47]
	v_add_f32_e32 v14, v14, v148
	v_add_f32_e32 v14, v14, v149
	v_add_f32_e32 v14, v14, v150
	v_add_f32_e32 v14, v14, v151
	s_setprio 2
	s_waitcnt lgkmcnt(0)
	s_barrier
	ds_read_b128 v[240:243], v195 offset:18432
	ds_read_b128 v[244:247], v195 offset:23040
	ds_read_b128 v[136:139], v195 offset:18464
	ds_read_b128 v[140:143], v195 offset:23072
	ds_read_b128 v[144:147], v195 offset:18496
	ds_read_b128 v[148:151], v195 offset:23104
	ds_read_b128 v[152:155], v195 offset:18528
	ds_read_b128 v[156:159], v195 offset:23136
	v_add_f32_e32 v1, v1, v160
	s_waitcnt lgkmcnt(6)
	v_mfma_f32_32x32x16_bf16 v[80:95], v[240:243], v[180:183], v[48:63]
	v_exp_f32_e32 v160, v112
	v_exp_f32_e32 v161, v113
	v_exp_f32_e32 v162, v114
	v_exp_f32_e32 v163, v115
	v_mfma_f32_32x32x16_bf16 v[64:79], v[244:247], v[180:183], v[48:63]
	v_exp_f32_e32 v164, v116
	v_exp_f32_e32 v165, v117
	v_exp_f32_e32 v166, v118
	v_exp_f32_e32 v167, v119
	s_waitcnt lgkmcnt(5)
	v_mfma_f32_32x32x16_bf16 v[80:95], v[136:139], v[176:179], v[80:95]
	v_exp_f32_e32 v184, v120
	v_exp_f32_e32 v185, v121
	v_exp_f32_e32 v186, v122
	v_exp_f32_e32 v187, v123
	s_waitcnt lgkmcnt(4)
	v_mfma_f32_32x32x16_bf16 v[64:79], v[140:143], v[176:179], v[64:79]
	v_exp_f32_e32 v136, v124
	v_exp_f32_e32 v137, v125
	v_exp_f32_e32 v138, v126
	v_exp_f32_e32 v139, v127
	s_waitcnt lgkmcnt(3)
	v_mfma_f32_32x32x16_bf16 v[80:95], v[144:147], v[172:175], v[80:95]
	v_exp_f32_e32 v140, v96
	v_exp_f32_e32 v141, v97
	v_exp_f32_e32 v142, v98
	v_exp_f32_e32 v143, v99
	s_waitcnt lgkmcnt(2)
	v_mfma_f32_32x32x16_bf16 v[64:79], v[148:151], v[172:175], v[64:79]
	v_exp_f32_e32 v144, v100
	v_exp_f32_e32 v145, v101
	v_exp_f32_e32 v146, v102
	v_exp_f32_e32 v147, v103
	s_waitcnt lgkmcnt(1)
	v_mfma_f32_32x32x16_bf16 v[80:95], v[152:155], v[168:171], v[80:95]
	v_exp_f32_e32 v148, v104
	v_exp_f32_e32 v149, v105
	v_exp_f32_e32 v150, v106
	v_exp_f32_e32 v151, v107
	s_waitcnt lgkmcnt(0)
	v_mfma_f32_32x32x16_bf16 v[64:79], v[156:159], v[168:171], v[64:79]
	v_exp_f32_e32 v152, v108
	v_exp_f32_e32 v153, v109
	v_exp_f32_e32 v154, v110
	v_exp_f32_e32 v155, v111
	s_cmp_gt_i32 s27, 2
	s_cselect_b32 s34, -3, 2
	s_waitcnt vmcnt(3)
	ds_write_b128 v208, v[128:131]
	v_add_u32_e32 v128, s29, v195
	ds_read_b128 v[240:243], v195 offset:27648
	ds_read_b128 v[244:247], v195 offset:32256
	ds_read_b128 v[96:99], v128 offset:41472
	ds_read_b128 v[100:103], v128 offset:36864
	ds_read_b128 v[104:107], v128 offset:36896
	ds_read_b128 v[108:111], v128 offset:41504
	ds_read_b128 v[116:119], v128 offset:36928
	ds_read_b128 v[120:123], v128 offset:41536
	ds_read_b128 v[124:127], v128 offset:36960
	ds_read_b128 v[128:131], v128 offset:41568
	s_add_i32 s34, s34, s27
	s_add_i32 s29, s13, -2
	s_mulk_i32 s34, 0x2400
	s_min_u32 s29, s29, s12
	v_add_u32_e32 v15, s34, v208
	s_lshl_b32 s92, s29, 13
	s_waitcnt vmcnt(2)
	ds_write_b128 v15, v[10:13] offset:36864
	s_add_u32 vcc_lo, s100, s92
	s_addc_u32 vcc_hi, s101, 0
	global_load_dwordx4 v[10:13], v248, vcc
	s_lshl_b32 s92, s28, 7
	v_add_f32_e32 v1, v1, v14
	s_add_u32 vcc_lo, s98, s92
	s_addc_u32 vcc_hi, s99, 0
	global_load_dwordx4 v[112:115], v249, vcc
	s_add_i32 s34, s27, 1
	s_setprio 1
	v_cvt_pk_bf16_f32 v132, v160, v161
	v_cvt_pk_bf16_f32 v133, v162, v163
	v_cvt_pk_bf16_f32 v134, v164, v165
	v_cvt_pk_bf16_f32 v135, v166, v167
	s_waitcnt lgkmcnt(7)
	s_nop 0
	v_mfma_f32_32x32x16_bf16 v[16:31], v[100:103], v[132:135], v[16:31]
	v_add_f32_e32 v14, v160, v161
	v_add_f32_e32 v14, v14, v162
	v_add_f32_e32 v14, v14, v163
	s_nop 0
	v_mfma_f32_32x32x16_bf16 v[32:47], v[96:99], v[132:135], v[32:47]
	v_cvt_pk_bf16_f32 v100, v184, v185
	v_cvt_pk_bf16_f32 v101, v186, v187
	v_cvt_pk_bf16_f32 v102, v136, v137
	v_cvt_pk_bf16_f32 v103, v138, v139
	v_add_f32_e32 v14, v14, v164
	v_add_f32_e32 v14, v14, v165
	v_add_f32_e32 v14, v14, v166
	v_add_f32_e32 v14, v14, v167
	s_waitcnt lgkmcnt(6)
	v_mfma_f32_32x32x16_bf16 v[16:31], v[104:107], v[100:103], v[16:31]
	v_add_f32_e32 v14, v14, v184
	v_add_f32_e32 v14, v14, v185
	v_add_f32_e32 v14, v14, v186
	v_add_f32_e32 v14, v14, v187
	s_waitcnt lgkmcnt(5)
	v_mfma_f32_32x32x16_bf16 v[32:47], v[108:111], v[100:103], v[32:47]
	v_cvt_pk_bf16_f32 v96, v140, v141
	v_cvt_pk_bf16_f32 v97, v142, v143
	v_cvt_pk_bf16_f32 v98, v144, v145
	v_cvt_pk_bf16_f32 v99, v146, v147
	v_add_f32_e32 v14, v14, v136
	v_add_f32_e32 v14, v14, v137
	v_add_f32_e32 v14, v14, v138
	v_add_f32_e32 v14, v14, v139
	s_waitcnt lgkmcnt(4)
	v_mfma_f32_32x32x16_bf16 v[16:31], v[116:119], v[96:99], v[16:31]
	v_add_f32_e32 v14, v14, v140
	v_add_f32_e32 v14, v14, v141
	v_add_f32_e32 v14, v14, v142
	v_add_f32_e32 v14, v14, v143
	s_waitcnt lgkmcnt(3)
	v_mfma_f32_32x32x16_bf16 v[32:47], v[120:123], v[96:99], v[32:47]
	v_cvt_pk_bf16_f32 v100, v148, v149
	v_cvt_pk_bf16_f32 v101, v150, v151
	v_cvt_pk_bf16_f32 v102, v152, v153
	v_cvt_pk_bf16_f32 v103, v154, v155
	v_add_f32_e32 v14, v14, v144
	v_add_f32_e32 v14, v14, v145
	v_add_f32_e32 v14, v14, v146
	v_add_f32_e32 v14, v14, v147
	s_waitcnt lgkmcnt(2)
	v_mfma_f32_32x32x16_bf16 v[16:31], v[124:127], v[100:103], v[16:31]
	v_add_f32_e32 v14, v14, v148
	v_add_f32_e32 v14, v14, v149
	v_add_f32_e32 v14, v14, v150
	v_add_f32_e32 v14, v14, v151
	s_waitcnt lgkmcnt(1)
	v_mfma_f32_32x32x16_bf16 v[32:47], v[128:131], v[100:103], v[32:47]
	v_add_f32_e32 v14, v14, v152
	v_add_f32_e32 v14, v14, v153
	v_add_f32_e32 v14, v14, v154
	v_add_f32_e32 v14, v14, v155
	s_setprio 0
	ds_read_b128 v[116:119], v195 offset:27680
	ds_read_b128 v[124:127], v195 offset:32288
	ds_read_b128 v[128:131], v195 offset:27712
	ds_read_b128 v[132:135], v195 offset:27744
	ds_read_b128 v[136:139], v195 offset:32320
	ds_read_b128 v[140:143], v195 offset:32352
	s_cmp_lg_u32 s27, 4
	s_cselect_b32 s27, s34, 0
	s_waitcnt lgkmcnt(6)
	v_mfma_f32_32x32x16_bf16 v[152:167], v[240:243], v[180:183], v[48:63]
	v_exp_f32_e32 v15, v80
	v_exp_f32_e32 v144, v81
	v_exp_f32_e32 v145, v82
	v_exp_f32_e32 v146, v83
	s_waitcnt lgkmcnt(5)
	v_mfma_f32_32x32x16_bf16 v[96:111], v[244:247], v[180:183], v[48:63]
	v_exp_f32_e32 v147, v84
	v_exp_f32_e32 v148, v85
	v_exp_f32_e32 v149, v86
	v_exp_f32_e32 v150, v87
	v_mfma_f32_32x32x16_bf16 v[152:167], v[116:119], v[176:179], v[152:167]
	v_exp_f32_e32 v120, v88
	v_exp_f32_e32 v121, v89
	v_exp_f32_e32 v122, v90
	v_exp_f32_e32 v123, v91
	s_waitcnt lgkmcnt(4)
	v_mfma_f32_32x32x16_bf16 v[96:111], v[124:127], v[176:179], v[96:111]
	v_exp_f32_e32 v151, v92
	v_exp_f32_e32 v184, v93
	v_exp_f32_e32 v185, v94
	v_exp_f32_e32 v186, v95
	s_waitcnt lgkmcnt(3)
	v_mfma_f32_32x32x16_bf16 v[152:167], v[128:131], v[172:175], v[152:167]
	v_exp_f32_e32 v124, v64
	v_exp_f32_e32 v125, v65
	v_exp_f32_e32 v126, v66
	v_exp_f32_e32 v127, v67
	s_waitcnt lgkmcnt(1)
	v_mfma_f32_32x32x16_bf16 v[96:111], v[136:139], v[172:175], v[96:111]
	v_exp_f32_e32 v128, v68
	v_exp_f32_e32 v129, v69
	v_exp_f32_e32 v130, v70
	v_exp_f32_e32 v131, v71
	v_mfma_f32_32x32x16_bf16 v[152:167], v[132:135], v[168:171], v[152:167]
	v_exp_f32_e32 v136, v72
	v_exp_f32_e32 v137, v73
	v_exp_f32_e32 v138, v74
	v_exp_f32_e32 v139, v75
	s_waitcnt lgkmcnt(0)
	v_mfma_f32_32x32x16_bf16 v[96:111], v[140:143], v[168:171], v[96:111]
	v_exp_f32_e32 v132, v76
	v_exp_f32_e32 v133, v77
	v_exp_f32_e32 v134, v78
	v_exp_f32_e32 v135, v79
	s_cmp_gt_i32 s27, 2
	s_cselect_b32 s28, -3, 2
	s_add_i32 s28, s28, s27
	s_mulk_i32 s28, 0x2400
	s_waitcnt vmcnt(3)
	ds_write_b128 v208, v[6:9] offset:9216
	v_add_u32_e32 v6, s28, v208
	s_add_i32 s28, s27, 1
	s_cmp_lg_u32 s27, 4
	s_cselect_b32 s27, s28, 0
	s_add_i32 s28, s13, -1
	s_min_u32 s28, s28, s12
	s_lshl_b32 s92, s28, 13
	s_waitcnt vmcnt(2)
	ds_write_b128 v6, v[2:5] offset:36864
	s_add_u32 vcc_lo, s100, s92
	s_addc_u32 vcc_hi, s101, 0
	global_load_dwordx4 v[6:9], v248, vcc
	s_lshl_b32 s92, s29, 7
	s_add_u32 vcc_lo, s98, s92
	s_addc_u32 vcc_hi, s99, 0
	global_load_dwordx4 v[2:5], v249, vcc
	s_nop 0
	s_mul_i32 s29, s27, 0x2400
	s_add_i32 s34, s29, 0xffffdc00
	s_cmp_lg_u32 s27, 0
	s_cselect_b32 s34, s34, 0x9000
	v_add_u32_e32 v92, s34, v195
	ds_read_b128 v[64:67], v92 offset:36864
	ds_read_b128 v[68:71], v92 offset:36896
	ds_read_b128 v[72:75], v92 offset:41472
	ds_read_b128 v[76:79], v92 offset:41504
	ds_read_b128 v[80:83], v92 offset:36928
	ds_read_b128 v[84:87], v92 offset:36960
	ds_read_b128 v[88:91], v92 offset:41536
	ds_read_b128 v[92:95], v92 offset:41568
	s_setprio 3
	v_cvt_pk_bf16_f32 v116, v15, v144
	v_cvt_pk_bf16_f32 v117, v145, v146
	v_cvt_pk_bf16_f32 v118, v147, v148
	v_cvt_pk_bf16_f32 v119, v149, v150
	s_waitcnt lgkmcnt(7)
	s_nop 0
	v_mfma_f32_32x32x16_bf16 v[16:31], v[64:67], v[116:119], v[16:31]
	v_add_f32_e32 v187, v15, v144
	v_add_f32_e32 v187, v187, v145
	v_add_f32_e32 v187, v187, v146
	s_waitcnt lgkmcnt(5)
	v_mfma_f32_32x32x16_bf16 v[32:47], v[72:75], v[116:119], v[32:47]
	v_cvt_pk_bf16_f32 v64, v120, v121
	v_cvt_pk_bf16_f32 v65, v122, v123
	v_cvt_pk_bf16_f32 v66, v151, v184
	v_cvt_pk_bf16_f32 v67, v185, v186
	v_add_f32_e32 v187, v187, v147
	v_add_f32_e32 v187, v187, v148
	v_add_f32_e32 v187, v187, v149
	v_add_f32_e32 v187, v187, v150
	s_nop 0
	v_mfma_f32_32x32x16_bf16 v[16:31], v[68:71], v[64:67], v[16:31]
	v_add_f32_e32 v187, v187, v120
	v_add_f32_e32 v187, v187, v121
	v_add_f32_e32 v187, v187, v122
	v_add_f32_e32 v187, v187, v123
	s_waitcnt lgkmcnt(4)
	v_mfma_f32_32x32x16_bf16 v[32:47], v[76:79], v[64:67], v[32:47]
	v_cvt_pk_bf16_f32 v68, v124, v125
	v_cvt_pk_bf16_f32 v69, v126, v127
	v_cvt_pk_bf16_f32 v70, v128, v129
	v_cvt_pk_bf16_f32 v71, v130, v131
	v_add_f32_e32 v187, v187, v151
	v_add_f32_e32 v187, v187, v184
	v_add_f32_e32 v187, v187, v185
	v_add_f32_e32 v187, v187, v186
	s_waitcnt lgkmcnt(3)
	v_mfma_f32_32x32x16_bf16 v[16:31], v[80:83], v[68:71], v[16:31]
	v_add_f32_e32 v187, v187, v124
	v_add_f32_e32 v187, v187, v125
	v_add_f32_e32 v187, v187, v126
	v_add_f32_e32 v187, v187, v127
	s_waitcnt lgkmcnt(1)
	v_mfma_f32_32x32x16_bf16 v[32:47], v[88:91], v[68:71], v[32:47]
	v_cvt_pk_bf16_f32 v64, v136, v137
	v_cvt_pk_bf16_f32 v65, v138, v139
	v_cvt_pk_bf16_f32 v66, v132, v133
	v_cvt_pk_bf16_f32 v67, v134, v135
	v_add_f32_e32 v187, v187, v128
	v_add_f32_e32 v187, v187, v129
	v_add_f32_e32 v187, v187, v130
	v_add_f32_e32 v187, v187, v131
	s_nop 0
	v_mfma_f32_32x32x16_bf16 v[16:31], v[84:87], v[64:67], v[16:31]
	v_add_f32_e32 v187, v187, v136
	v_add_f32_e32 v187, v187, v137
	v_add_f32_e32 v187, v187, v138
	v_add_f32_e32 v187, v187, v139
	s_waitcnt lgkmcnt(0)
	v_mfma_f32_32x32x16_bf16 v[32:47], v[92:95], v[64:67], v[32:47]
	v_add_f32_e32 v187, v187, v132
	v_add_f32_e32 v187, v187, v133
	v_add_f32_e32 v187, v187, v134
	v_add_f32_e32 v187, v187, v135
	s_setprio 2
	s_waitcnt lgkmcnt(0)
	s_barrier
	ds_read_b128 v[240:243], v195
	ds_read_b128 v[244:247], v195 offset:4608
	ds_read_b128 v[72:75], v195 offset:32
	ds_read_b128 v[76:79], v195 offset:4640
	ds_read_b128 v[80:83], v195 offset:64
	ds_read_b128 v[84:87], v195 offset:4672
	ds_read_b128 v[88:91], v195 offset:96
	ds_read_b128 v[92:95], v195 offset:4704
	v_add_f32_e32 v1, v1, v14
	s_waitcnt lgkmcnt(6)
	v_mfma_f32_32x32x16_bf16 v[136:151], v[240:243], v[180:183], v[48:63]
	v_exp_f32_e32 v14, v152
	v_exp_f32_e32 v15, v153
	v_exp_f32_e32 v116, v154
	v_exp_f32_e32 v117, v155
	v_mfma_f32_32x32x16_bf16 v[120:135], v[244:247], v[180:183], v[48:63]
	v_exp_f32_e32 v118, v156
	v_exp_f32_e32 v119, v157
	v_exp_f32_e32 v184, v158
	v_exp_f32_e32 v185, v159
	s_waitcnt lgkmcnt(5)
	v_mfma_f32_32x32x16_bf16 v[136:151], v[72:75], v[176:179], v[136:151]
	v_exp_f32_e32 v186, v160
	v_exp_f32_e32 v210, v161
	v_exp_f32_e32 v211, v162
	v_exp_f32_e32 v212, v163
	s_waitcnt lgkmcnt(4)
	v_mfma_f32_32x32x16_bf16 v[120:135], v[76:79], v[176:179], v[120:135]
	v_exp_f32_e32 v160, v164
	v_exp_f32_e32 v161, v165
	v_exp_f32_e32 v162, v166
	v_exp_f32_e32 v163, v167
	s_waitcnt lgkmcnt(3)
	v_mfma_f32_32x32x16_bf16 v[136:151], v[80:83], v[172:175], v[136:151]
	v_exp_f32_e32 v164, v96
	v_exp_f32_e32 v165, v97
	v_exp_f32_e32 v166, v98
	v_exp_f32_e32 v167, v99
	s_waitcnt lgkmcnt(2)
	v_mfma_f32_32x32x16_bf16 v[120:135], v[84:87], v[172:175], v[120:135]
	v_exp_f32_e32 v96, v100
	v_exp_f32_e32 v97, v101
	v_exp_f32_e32 v98, v102
	v_exp_f32_e32 v99, v103
	s_waitcnt lgkmcnt(1)
	v_mfma_f32_32x32x16_bf16 v[136:151], v[88:91], v[168:171], v[136:151]
	v_exp_f32_e32 v100, v104
	v_exp_f32_e32 v101, v105
	v_exp_f32_e32 v102, v106
	v_exp_f32_e32 v103, v107
	s_waitcnt lgkmcnt(0)
	v_mfma_f32_32x32x16_bf16 v[120:135], v[92:95], v[168:171], v[120:135]
	v_exp_f32_e32 v104, v108
	v_exp_f32_e32 v105, v109
	v_exp_f32_e32 v106, v110
	v_exp_f32_e32 v107, v111
	s_cmp_gt_i32 s27, 2
	s_cselect_b32 s34, -3, 2
	s_add_i32 s34, s34, s27
	s_mulk_i32 s34, 0x2400
	v_add_u32_e32 v88, s29, v195
	s_min_u32 s29, s13, s12
	s_waitcnt vmcnt(3)
	ds_write_b128 v208, v[10:13] offset:18432
	v_add_u32_e32 v10, s34, v208
	s_lshl_b32 s92, s29, 13
	s_waitcnt vmcnt(2)
	ds_write_b128 v10, v[112:115] offset:36864
	ds_read_b128 v[240:243], v195 offset:9216
	ds_read_b128 v[244:247], v195 offset:13824
	ds_read_b128 v[10:13], v88 offset:41472
	ds_read_b128 v[64:67], v88 offset:36864
	ds_read_b128 v[68:71], v88 offset:36896
	ds_read_b128 v[72:75], v88 offset:41504
	ds_read_b128 v[76:79], v88 offset:36928
	ds_read_b128 v[80:83], v88 offset:41536
	ds_read_b128 v[84:87], v88 offset:36960
	ds_read_b128 v[88:91], v88 offset:41568
	s_add_u32 vcc_lo, s100, s92
	s_addc_u32 vcc_hi, s101, 0
	global_load_dwordx4 v[152:155], v248, vcc
	s_lshl_b32 s92, s28, 7
	s_add_u32 vcc_lo, s98, s92
	s_addc_u32 vcc_hi, s99, 0
	global_load_dwordx4 v[156:159], v249, vcc
	v_add_f32_e32 v1, v1, v187
	s_setprio 1
	v_mov_b32_e32 v109, v136
	v_cvt_pk_bf16_f32 v92, v14, v15
	v_cvt_pk_bf16_f32 v93, v116, v117
	v_cvt_pk_bf16_f32 v94, v118, v119
	v_cvt_pk_bf16_f32 v95, v184, v185
	s_waitcnt lgkmcnt(6)
	s_nop 0
	v_mfma_f32_32x32x16_bf16 v[16:31], v[64:67], v[92:95], v[16:31]
	v_max3_f32 v109, v109, v137, v138
	v_max3_f32 v109, v109, v139, v140
	v_add_f32_e32 v108, v14, v15
	v_add_f32_e32 v108, v108, v116
	v_add_f32_e32 v108, v108, v117
	s_nop 0
	v_mfma_f32_32x32x16_bf16 v[32:47], v[10:13], v[92:95], v[32:47]
	v_cvt_pk_bf16_f32 v64, v186, v210
	v_cvt_pk_bf16_f32 v65, v211, v212
	v_cvt_pk_bf16_f32 v66, v160, v161
	v_cvt_pk_bf16_f32 v67, v162, v163
	v_max3_f32 v109, v109, v141, v142
	v_max3_f32 v109, v109, v143, v144
	v_add_f32_e32 v108, v108, v118
	v_add_f32_e32 v108, v108, v119
	v_add_f32_e32 v108, v108, v184
	v_add_f32_e32 v108, v108, v185
	s_waitcnt lgkmcnt(5)
	v_mfma_f32_32x32x16_bf16 v[16:31], v[68:71], v[64:67], v[16:31]
	v_max3_f32 v109, v109, v145, v146
	v_max3_f32 v109, v109, v147, v148
	v_add_f32_e32 v108, v108, v186
	v_add_f32_e32 v108, v108, v210
	v_add_f32_e32 v108, v108, v211
	v_add_f32_e32 v108, v108, v212
	s_waitcnt lgkmcnt(4)
	v_mfma_f32_32x32x16_bf16 v[32:47], v[72:75], v[64:67], v[32:47]
	v_cvt_pk_bf16_f32 v10, v164, v165
	v_cvt_pk_bf16_f32 v11, v166, v167
	v_cvt_pk_bf16_f32 v12, v96, v97
	v_cvt_pk_bf16_f32 v13, v98, v99
	v_max3_f32 v109, v109, v149, v150
	v_max3_f32 v109, v109, v151, v120
	v_add_f32_e32 v108, v108, v160
	v_add_f32_e32 v108, v108, v161
	v_add_f32_e32 v108, v108, v162
	v_add_f32_e32 v108, v108, v163
	s_waitcnt lgkmcnt(3)
	v_mfma_f32_32x32x16_bf16 v[16:31], v[76:79], v[10:13], v[16:31]
	v_max3_f32 v109, v109, v121, v122
	v_max3_f32 v109, v109, v123, v124
	v_add_f32_e32 v108, v108, v164
	v_add_f32_e32 v108, v108, v165
	v_add_f32_e32 v108, v108, v166
	v_add_f32_e32 v108, v108, v167
	s_waitcnt lgkmcnt(2)
	v_mfma_f32_32x32x16_bf16 v[32:47], v[80:83], v[10:13], v[32:47]
	v_cvt_pk_bf16_f32 v64, v100, v101
	v_cvt_pk_bf16_f32 v65, v102, v103
	v_cvt_pk_bf16_f32 v66, v104, v105
	v_cvt_pk_bf16_f32 v67, v106, v107
	v_max3_f32 v109, v109, v125, v126
	v_max3_f32 v109, v109, v127, v128
	v_add_f32_e32 v108, v108, v96
	v_add_f32_e32 v108, v108, v97
	v_add_f32_e32 v108, v108, v98
	v_add_f32_e32 v108, v108, v99
	s_waitcnt lgkmcnt(1)
	v_mfma_f32_32x32x16_bf16 v[16:31], v[84:87], v[64:67], v[16:31]
	v_max3_f32 v109, v109, v129, v130
	v_max3_f32 v109, v109, v131, v132
	v_add_f32_e32 v108, v108, v100
	v_add_f32_e32 v108, v108, v101
	v_add_f32_e32 v108, v108, v102
	v_add_f32_e32 v108, v108, v103
	s_waitcnt lgkmcnt(0)
	v_mfma_f32_32x32x16_bf16 v[32:47], v[88:91], v[64:67], v[32:47]
	v_max3_f32 v109, v109, v133, v134
	v_max3_f32 v109, v109, v135, v135
	v_add_f32_e32 v108, v108, v104
	v_add_f32_e32 v108, v108, v105
	v_add_f32_e32 v108, v108, v106
	v_add_f32_e32 v108, v108, v107
	s_setprio 0
	ds_read_b128 v[164:167], v195 offset:9248
	ds_read_b128 v[160:163], v195 offset:13856
	ds_read_b128 v[74:77], v195 offset:9280
	ds_read_b128 v[66:69], v195 offset:9312
	ds_read_b128 v[70:73], v195 offset:13888
	ds_read_b128 v[10:13], v195 offset:13920
	v_add_f32_e32 v64, v1, v108
	v_mov_b32_e32 v1, v109
	s_nop 1
	v_permlane32_swap_b32_e32 v109, v1
	v_max_f32_e32 v1, v1, v1
	v_max_f32_e32 v14, v109, v109
	v_max_f32_e32 v1, v14, v1
	v_cmp_lt_f32_e32 vcc, s52, v1
	s_cbranch_vccz .LBB0_663
	v_max_f32_e32 v1, v1, v1
	v_max_f32_e32 v14, 0, v1
	v_add_f32_e32 v209, v209, v14
	v_xor_b32_e32 v48, 0x80000000, v209
	v_pk_add_f32 v[136:137], v[136:137], v[14:15] op_sel_hi:[1,0] neg_lo:[0,1] neg_hi:[0,1]
	v_pk_add_f32 v[120:121], v[120:121], v[14:15] op_sel_hi:[1,0] neg_lo:[0,1] neg_hi:[0,1]
	v_pk_add_f32 v[138:139], v[138:139], v[14:15] op_sel_hi:[1,0] neg_lo:[0,1] neg_hi:[0,1]
	v_pk_add_f32 v[122:123], v[122:123], v[14:15] op_sel_hi:[1,0] neg_lo:[0,1] neg_hi:[0,1]
	v_pk_add_f32 v[140:141], v[140:141], v[14:15] op_sel_hi:[1,0] neg_lo:[0,1] neg_hi:[0,1]
	v_pk_add_f32 v[124:125], v[124:125], v[14:15] op_sel_hi:[1,0] neg_lo:[0,1] neg_hi:[0,1]
	v_pk_add_f32 v[142:143], v[142:143], v[14:15] op_sel_hi:[1,0] neg_lo:[0,1] neg_hi:[0,1]
	v_pk_add_f32 v[126:127], v[126:127], v[14:15] op_sel_hi:[1,0] neg_lo:[0,1] neg_hi:[0,1]
	v_pk_add_f32 v[144:145], v[144:145], v[14:15] op_sel_hi:[1,0] neg_lo:[0,1] neg_hi:[0,1]
	v_pk_add_f32 v[128:129], v[128:129], v[14:15] op_sel_hi:[1,0] neg_lo:[0,1] neg_hi:[0,1]
	v_pk_add_f32 v[146:147], v[146:147], v[14:15] op_sel_hi:[1,0] neg_lo:[0,1] neg_hi:[0,1]
	v_pk_add_f32 v[130:131], v[130:131], v[14:15] op_sel_hi:[1,0] neg_lo:[0,1] neg_hi:[0,1]
	v_pk_add_f32 v[148:149], v[148:149], v[14:15] op_sel_hi:[1,0] neg_lo:[0,1] neg_hi:[0,1]
	v_pk_add_f32 v[132:133], v[132:133], v[14:15] op_sel_hi:[1,0] neg_lo:[0,1] neg_hi:[0,1]
	v_pk_add_f32 v[150:151], v[150:151], v[14:15] op_sel_hi:[1,0] neg_lo:[0,1] neg_hi:[0,1]
	v_pk_add_f32 v[134:135], v[134:135], v[14:15] op_sel_hi:[1,0] neg_lo:[0,1] neg_hi:[0,1]
	v_exp_f32_e64 v14, -v14
	v_mov_b32_e32 v49, v48
	v_mov_b32_e32 v50, v48
	v_mov_b32_e32 v51, v48
	v_mov_b32_e32 v52, v48
	v_mov_b32_e32 v53, v48
	v_mov_b32_e32 v54, v48
	v_mov_b32_e32 v55, v48
	v_mov_b32_e32 v56, v48
	v_mov_b32_e32 v57, v48
	v_mov_b32_e32 v58, v48
	v_mov_b32_e32 v59, v48
	v_mov_b32_e32 v60, v48
	v_mov_b32_e32 v61, v48
	v_mov_b32_e32 v62, v48
	v_mov_b32_e32 v63, v48
	s_nop 11
	v_pk_mul_f32 v[30:31], v[30:31], v[14:15] op_sel_hi:[1,0]
	v_pk_mul_f32 v[28:29], v[28:29], v[14:15] op_sel_hi:[1,0]
	v_pk_mul_f32 v[26:27], v[26:27], v[14:15] op_sel_hi:[1,0]
	v_pk_mul_f32 v[24:25], v[24:25], v[14:15] op_sel_hi:[1,0]
	v_pk_mul_f32 v[22:23], v[22:23], v[14:15] op_sel_hi:[1,0]
	v_pk_mul_f32 v[20:21], v[20:21], v[14:15] op_sel_hi:[1,0]
	v_pk_mul_f32 v[18:19], v[18:19], v[14:15] op_sel_hi:[1,0]
	v_pk_mul_f32 v[16:17], v[16:17], v[14:15] op_sel_hi:[1,0]
	v_pk_mul_f32 v[46:47], v[46:47], v[14:15] op_sel_hi:[1,0]
	v_pk_mul_f32 v[44:45], v[44:45], v[14:15] op_sel_hi:[1,0]
	v_pk_mul_f32 v[42:43], v[42:43], v[14:15] op_sel_hi:[1,0]
	v_pk_mul_f32 v[40:41], v[40:41], v[14:15] op_sel_hi:[1,0]
	v_pk_mul_f32 v[38:39], v[38:39], v[14:15] op_sel_hi:[1,0]
	v_pk_mul_f32 v[36:37], v[36:37], v[14:15] op_sel_hi:[1,0]
	v_pk_mul_f32 v[34:35], v[34:35], v[14:15] op_sel_hi:[1,0]
	v_pk_mul_f32 v[32:33], v[32:33], v[14:15] op_sel_hi:[1,0]
	v_mul_f32_e32 v64, v64, v14
